# attention schedule variant: NPRE=4
# baseline (speedup 1.0000x reference)
; __device__ __forceinline__ unsigned cvtpk(float lo, float hi) { f32x2 v = {lo, hi}; bf16x2_t b = __builtin_convertvector(v, bf16x2_t); return *(unsigned*)&b; }
; __device__ __forceinline__ float lo16(unsigned w) { return __uint_as_float(w << 16); }
; __device__ __forceinline__ float hi16(unsigned w) { return __uint_as_float(w & 0xffff0000u); }
; #define SWAIT() asm volatile("s_waitcnt vmcnt(3)" ::: "memory")
; __device__ void phase_attn(const Params& p, char* lds) {
;     ...
;   for (int it = slot; it < nitems / 8; it += per) {
;     const int pair = (it >> 5) * 8 + xcd, qblk = it & 31;
;     const int b = pair >> 4, h = pair & 15;
;     const size_t row0 = (size_t)b * TL;
;     const size_t qrow = row0 + qblk * 256 + wid * 32 + r32;
;     const bf16_t* Kh = KVg + row0 * 2048 + h * 128;
;     const bf16_t* Kp = KPg + row0 * 32;
;     float m_reg = 0.f, l_reg = 0.f;
;     f32x16 o[2];
; #pragma unroll
;     for (int dd = 0; dd < 2; ++dd)
; #pragma unroll
;       for (int r = 0; r < 16; ++r) o[dd][r] = 0.f;
;     bf16x8 qr[6];
;     {
;       const bf16_t* Qw = Qg + qrow * 1536 + h * 96 + hi * 8;
; #pragma unroll
;       for (int d0 = 0; d0 < 6; ++d0) qr[d0] = *(const bf16x8*)(Qw + d0 * 16);
;       const int t = qblk * 256 + wid * 32 + r32;
;       const f32x2* tb = rope + (hi ? (t & 63) : (t >> 6)) * 8;
;       const u32x4 x1 = *(const u32x4*)&qr[4], x2 = *(const u32x4*)&qr[5];
;       u32x4 n1, n2;
; #pragma unroll
;       for (int q = 0; q < 4; ++q) {
;         const f32x2 csA = tb[2 * q], csB = tb[2 * q + 1];
;         const float a0 = lo16(x1[q]), a1 = hi16(x1[q]), b0 = lo16(x2[q]), b1 = hi16(x2[q]);
;         n1[q] = cvtpk(a0 * csA[0] - b0 * csA[1], a1 * csB[0] - b1 * csB[1]);
;         n2[q] = cvtpk(a0 * csA[1] + b0 * csA[0], a1 * csB[1] + b1 * csB[0]);
;       }
;       qr[4] = *(bf16x8*)&n1; qr[5] = *(bf16x8*)&n2;
;     }
;     struct { bf16x8 vs, ks, ps; } sr_[2];
;     ...
;     f32x16 pA0, pA1, pB0, pB1; float alA, alB; bf16x8 pa0, pa1, pa2, pa3;
;     constexpr int NT = TL / 64;
;     SLOAD(0, 0); asm volatile("s_waitcnt vmcnt(0)" ::: "memory"); SWRITE(0, 0); __syncthreads();
;     at_qkt(pA0, pA1, K_lds, qr, r32, hi, 0.f); at_partialSM(pA0, pA1, m_reg, alA, true);
;     SLOAD(1, 64); SLOAD(0, 128);
;     SWAIT(); SWRITE(1, 1); __syncthreads();
.Lat_item:
	s_lshr_b32 s16, s12, 5
	s_lshl_b32 s16, s16, 3
	s_add_i32 s16, s16, s43
	s_and_b32 s20, s12, 31
	s_lshr_b32 s22, s16, 4
	s_and_b32 s21, s16, 15
	s_mul_i32 s17, s22, 0x2100000
	s_lshl_b32 s18, s21, 8
	s_add_i32 s17, s17, s18
	s_add_u32 s17, s17, 0x29400000
	s_add_u32 s4, s86, s17
	s_addc_u32 s5, s87, 0
	s_mul_i32 s17, s22, 0x84000
	s_add_u32 s17, s17, 0x1de80000
	s_add_u32 s6, s86, s17
	s_addc_u32 s7, s87, 0
	s_mul_i32 s17, s22, 0x2100
	s_lshl_b32 s18, s20, 8
	s_add_i32 s17, s17, s18
	s_mul_i32 s18, s17, 0xc00
	s_mul_i32 s19, s21, 0xc0
	s_add_i32 s18, s18, s19
	s_add_u32 s18, s18, 0x8400000
	s_add_u32 s10, s86, s18
	s_addc_u32 s11, s87, 0
	s_lshl_b32 s18, s17, 11
	s_lshl_b32 s19, s21, 7
	s_add_i32 s18, s18, s19
	s_add_u32 s18, s18, 0x21000000
	s_add_u32 s28, s86, s18
	s_addc_u32 s29, s87, 0
	global_load_dwordx4 v[80:83], v234, s[10:11] offset:0
	global_load_dwordx4 v[84:87], v234, s[10:11] offset:32
	global_load_dwordx4 v[88:91], v234, s[10:11] offset:64
	global_load_dwordx4 v[92:95], v234, s[10:11] offset:96
	global_load_dwordx4 v[96:99], v234, s[10:11] offset:128
	global_load_dwordx4 v[100:103], v234, s[10:11] offset:160
	s_and_b32 s16, s14, 1
	s_lshl_b32 s16, s16, 5
	v_and_b32_e32 v183, 31, v178
	v_add_u32_e32 v183, s16, v183
	v_lshlrev_b32_e32 v183, 6, v183
	s_lshl_b32 s16, s20, 2
	s_lshr_b32 s17, s14, 1
	s_add_i32 s16, s16, s17
	s_lshl_b32 s16, s16, 6
	v_mov_b32_e32 v228, s16
	v_and_b32_e32 v229, 32, v178
	v_cmp_ne_u32_e32 vcc, 0, v229
	s_nop 1
	v_cndmask_b32_e32 v183, v228, v183, vcc
	global_load_dwordx4 v[32:35], v183, s[34:35] offset:0
	global_load_dwordx4 v[36:39], v183, s[34:35] offset:16
	global_load_dwordx4 v[40:43], v183, s[34:35] offset:32
	global_load_dwordx4 v[44:47], v183, s[34:35] offset:48
	s_barrier
	global_load_dwordx4 v[120:123], v129, s[4:5]
	global_load_dwordx4 v[124:127], v129, s[4:5] offset:128
	global_load_dwordx4 v[132:135], v130, s[6:7]
	s_add_u32 s4, s4, 0x40000
	s_addc_u32 s5, s5, 0
	s_add_u32 s6, s6, 0x1000
	s_addc_u32 s7, s7, 0
	global_load_dwordx4 v[136:139], v129, s[4:5]
	global_load_dwordx4 v[140:143], v129, s[4:5] offset:128
	global_load_dwordx4 v[144:147], v130, s[6:7]
	s_add_u32 s4, s4, 0x40000
	s_addc_u32 s5, s5, 0
	s_add_u32 s6, s6, 0x1000
	s_addc_u32 s7, s7, 0
	s_waitcnt vmcnt(0)
	ds_write_b128 v167, v[120:123] offset:0
	ds_write_b128 v131, v[124:127] offset:0
	ds_write_b128 v169, v[132:135] offset:0
	ds_write_b128 v167, v[136:139] offset:13312
	ds_write_b128 v131, v[140:143] offset:16384
	ds_write_b128 v169, v[144:147] offset:13312
	s_waitcnt lgkmcnt(0)
	global_load_dwordx4 v[120:123], v129, s[4:5]
	global_load_dwordx4 v[124:127], v129, s[4:5] offset:128
	global_load_dwordx4 v[132:135], v130, s[6:7]
	s_add_u32 s4, s4, 0x40000
	s_addc_u32 s5, s5, 0
	s_add_u32 s6, s6, 0x1000
	s_addc_u32 s7, s7, 0
	v_lshlrev_b32_e32 v175, 16, v96
	v_and_b32_e32 v183, 0xffff0000, v96
	v_lshlrev_b32_e32 v228, 16, v100
	v_and_b32_e32 v229, 0xffff0000, v100
	v_mul_f32_e32 v230, v228, v33
	v_mul_f32_e32 v174, v229, v35
	v_fma_f32 v230, v175, v32, -v230
	v_fma_f32 v174, v183, v34, -v174
	v_mul_f32_e32 v175, v175, v33
	v_mul_f32_e32 v183, v183, v35
	v_fma_f32 v175, v228, v32, v175
	v_fma_f32 v183, v229, v34, v183
	v_cvt_pk_bf16_f32 v96, v230, v174
	v_cvt_pk_bf16_f32 v100, v175, v183
	v_lshlrev_b32_e32 v175, 16, v97
	v_and_b32_e32 v183, 0xffff0000, v97
	v_lshlrev_b32_e32 v228, 16, v101
	v_and_b32_e32 v229, 0xffff0000, v101
	v_mul_f32_e32 v230, v228, v37
	v_mul_f32_e32 v174, v229, v39
	v_fma_f32 v230, v175, v36, -v230
	v_fma_f32 v174, v183, v38, -v174
	v_mul_f32_e32 v175, v175, v37
	v_mul_f32_e32 v183, v183, v39
	v_fma_f32 v175, v228, v36, v175
	v_fma_f32 v183, v229, v38, v183
	v_cvt_pk_bf16_f32 v97, v230, v174
	v_cvt_pk_bf16_f32 v101, v175, v183
	v_lshlrev_b32_e32 v175, 16, v98
	v_and_b32_e32 v183, 0xffff0000, v98
	v_lshlrev_b32_e32 v228, 16, v102
	v_and_b32_e32 v229, 0xffff0000, v102
	v_mul_f32_e32 v230, v228, v41
	v_mul_f32_e32 v174, v229, v43
	v_fma_f32 v230, v175, v40, -v230
	v_fma_f32 v174, v183, v42, -v174
	v_mul_f32_e32 v175, v175, v41
	v_mul_f32_e32 v183, v183, v43
	v_fma_f32 v175, v228, v40, v175
	v_fma_f32 v183, v229, v42, v183
	v_cvt_pk_bf16_f32 v98, v230, v174
	v_cvt_pk_bf16_f32 v102, v175, v183
	v_lshlrev_b32_e32 v175, 16, v99
	v_and_b32_e32 v183, 0xffff0000, v99
	v_lshlrev_b32_e32 v228, 16, v103
	v_and_b32_e32 v229, 0xffff0000, v103
	v_mul_f32_e32 v230, v228, v45
	v_mul_f32_e32 v174, v229, v47
	v_fma_f32 v230, v175, v44, -v230
	v_fma_f32 v174, v183, v46, -v174
	v_mul_f32_e32 v175, v175, v45
	v_mul_f32_e32 v183, v183, v47
	v_fma_f32 v175, v228, v44, v175
	v_fma_f32 v183, v229, v46, v183
	v_cvt_pk_bf16_f32 v99, v230, v174
	v_cvt_pk_bf16_f32 v103, v175, v183
	v_mov_b32_e32 v0, 0
	v_mov_b32_e32 v1, 0
	v_mov_b32_e32 v2, 0
	v_mov_b32_e32 v3, 0
	v_mov_b32_e32 v4, 0
	v_mov_b32_e32 v5, 0
	v_mov_b32_e32 v6, 0
	v_mov_b32_e32 v7, 0
	v_mov_b32_e32 v8, 0
	v_mov_b32_e32 v9, 0
	v_mov_b32_e32 v10, 0
	v_mov_b32_e32 v11, 0
	v_mov_b32_e32 v12, 0
	v_mov_b32_e32 v13, 0
	v_mov_b32_e32 v14, 0
	v_mov_b32_e32 v15, 0
	v_mov_b32_e32 v16, 0
	v_mov_b32_e32 v17, 0
	v_mov_b32_e32 v18, 0
	v_mov_b32_e32 v19, 0
	v_mov_b32_e32 v20, 0
	v_mov_b32_e32 v21, 0
	v_mov_b32_e32 v22, 0
	v_mov_b32_e32 v23, 0
	v_mov_b32_e32 v24, 0
	v_mov_b32_e32 v25, 0
	v_mov_b32_e32 v26, 0
	v_mov_b32_e32 v27, 0
	v_mov_b32_e32 v28, 0
	v_mov_b32_e32 v29, 0
	v_mov_b32_e32 v30, 0
	v_mov_b32_e32 v31, 0
	v_mov_b32_e32 v173, 0
	s_barrier
	ds_read_b128 v[184:187], v170 offset:0
	ds_read_b128 v[188:191], v170 offset:6656
	ds_read_b128 v[192:195], v170 offset:32
	ds_read_b128 v[196:199], v170 offset:6688
	ds_read_b128 v[200:203], v170 offset:64
	ds_read_b128 v[204:207], v170 offset:6720
	ds_read_b128 v[208:211], v170 offset:96
	ds_read_b128 v[212:215], v170 offset:6752
	s_cmp_eq_u32 s15, 0
	s_cbranch_scc1 .Lat_nostag
	s_barrier
; __device__ __forceinline__ void at_partialSM(f32x16& p0, f32x16& p1, float& m_reg, float& alpha, bool force) {
;   float pm = p0[0];
; #pragma unroll
;   for (int r = 1; r < 16; ++r) pm = fmaxf(pm, p0[r]);
; #pragma unroll
;   for (int r = 0; r < 16; ++r) pm = fmaxf(pm, p1[r]);
;   { auto rr = __builtin_amdgcn_permlane32_swap(__float_as_uint(pm), __float_as_uint(pm), false, false);
;     pm = fmaxf(__uint_as_float(rr[0]), __uint_as_float(rr[1])); }
;   if (__builtin_expect(!force && __all(pm <= AT_THR * 1.4426950408889634f), 1)) { alpha = 1.f; }
;   else {
;     const float dlt = force ? pm : fmaxf(pm, 0.f);
;     alpha = force ? 1.f : __builtin_amdgcn_exp2f(-dlt); m_reg += dlt;
; #pragma unroll
;     for (int r = 0; r < 16; ++r) { p0[r] -= dlt; p1[r] -= dlt; }
;   }
; #pragma unroll
;   for (int r = 0; r < 16; ++r) p0[r] = __builtin_amdgcn_exp2f(p0[r]);
; }
; __device__ __forceinline__ void at_finishSM(f32x16& p0, f32x16& p1, float alpha, float& l_reg, bf16x8& pa0, bf16x8& pa1, bf16x8& pa2, bf16x8& pa3) {
; #pragma unroll
;   for (int r = 0; r < 16; ++r) p1[r] = __builtin_amdgcn_exp2f(p1[r]);
;   float ps = 0;
; #pragma unroll
;   for (int r = 0; r < 16; ++r) ps += p0[r];
; #pragma unroll
;   for (int r = 0; r < 16; ++r) ps += p1[r];
;   { auto rr = __builtin_amdgcn_permlane32_swap(__float_as_uint(ps), __float_as_uint(ps), false, false);
;     ps = __uint_as_float(rr[0]) + __uint_as_float(rr[1]); }
;   l_reg = l_reg * alpha + ps;
;     ...
;   PK4(p0, 0, pa0); PK4(p0, 8, pa1); PK4(p1, 0, pa2); PK4(p1, 8, pa3);
;     ...
; }
; __device__ __forceinline__ void at_qkt(f32x16& p0, f32x16& p1, const char* Ks, const bf16x8* qr, int r32, int hi, float negm) {
; #pragma unroll
;   for (int r = 0; r < 16; ++r) { p0[r] = negm; p1[r] = negm; }
; #pragma unroll
;   for (int d0 = 0; d0 < 6; ++d0) {
;     const bf16x8 b0 = *(const bf16x8*)(Ks + r32 * AT_KROW + d0 * 32 + hi * 16);
;     const bf16x8 b1 = *(const bf16x8*)(Ks + (32 + r32) * AT_KROW + d0 * 32 + hi * 16);
;     p0 = MFMA(b0, qr[d0], p0);
;     p1 = MFMA(b1, qr[d0], p1);
;   }
; }
; __device__ void phase_attn(const Params& p, char* lds) {
;     ...
;     SLOAD(0, 0); asm volatile("s_waitcnt vmcnt(0)" ::: "memory"); SWRITE(0, 0); __syncthreads();
;     at_qkt(pA0, pA1, K_lds, qr, r32, hi, 0.f); at_partialSM(pA0, pA1, m_reg, alA, true);
;     SLOAD(1, 64); SLOAD(0, 128);
;     SWAIT(); SWRITE(1, 1); __syncthreads();
.Lat_nostag:
	s_waitcnt lgkmcnt(6)
	v_mfma_f32_32x32x16_bf16 v[32:47], v[184:187], v[80:83], 0
	v_mfma_f32_32x32x16_bf16 v[48:63], v[188:191], v[80:83], 0
	ds_read_b128 v[184:187], v170 offset:128
	ds_read_b128 v[188:191], v170 offset:6784
	s_waitcnt lgkmcnt(6)
	v_mfma_f32_32x32x16_bf16 v[32:47], v[192:195], v[84:87], v[32:47]
	v_mfma_f32_32x32x16_bf16 v[48:63], v[196:199], v[84:87], v[48:63]
	ds_read_b128 v[192:195], v170 offset:160
	ds_read_b128 v[196:199], v170 offset:6816
	s_waitcnt lgkmcnt(6)
	v_mfma_f32_32x32x16_bf16 v[32:47], v[200:203], v[88:91], v[32:47]
	v_mfma_f32_32x32x16_bf16 v[48:63], v[204:207], v[88:91], v[48:63]
	s_waitcnt lgkmcnt(4)
	v_mfma_f32_32x32x16_bf16 v[32:47], v[208:211], v[92:95], v[32:47]
	v_mfma_f32_32x32x16_bf16 v[48:63], v[212:215], v[92:95], v[48:63]
	s_waitcnt lgkmcnt(2)
	v_mfma_f32_32x32x16_bf16 v[32:47], v[184:187], v[96:99], v[32:47]
	v_mfma_f32_32x32x16_bf16 v[48:63], v[188:191], v[96:99], v[48:63]
	s_waitcnt lgkmcnt(0)
	v_mfma_f32_32x32x16_bf16 v[32:47], v[192:195], v[100:103], v[32:47]
	v_mfma_f32_32x32x16_bf16 v[48:63], v[196:199], v[100:103], v[48:63]
	s_nop 11
	v_max3_f32 v174, v32, v33, v34
	v_max3_f32 v175, v48, v49, v50
	v_max3_f32 v174, v174, v35, v36
	v_max3_f32 v175, v175, v51, v52
	v_max3_f32 v174, v174, v37, v38
	v_max3_f32 v175, v175, v53, v54
	v_max3_f32 v174, v174, v39, v40
	v_max3_f32 v175, v175, v55, v56
	v_max3_f32 v174, v174, v41, v42
	v_max3_f32 v175, v175, v57, v58
	v_max3_f32 v174, v174, v43, v44
	v_max3_f32 v175, v175, v59, v60
	v_max3_f32 v174, v174, v45, v46
	v_max3_f32 v175, v175, v61, v62
	v_max3_f32 v174, v174, v47, v63
	v_max_f32_e32 v174, v174, v175
	v_mov_b32_e32 v175, v174
	s_nop 1
	v_permlane32_swap_b32_e32 v174, v175
	v_max_f32_e32 v174, v174, v175
	s_barrier
	v_mov_b32_e32 v172, v174
	v_sub_f32_e32 v32, v32, v174
	v_sub_f32_e32 v48, v48, v174
	v_sub_f32_e32 v33, v33, v174
	v_sub_f32_e32 v49, v49, v174
	v_sub_f32_e32 v34, v34, v174
	v_sub_f32_e32 v50, v50, v174
	v_sub_f32_e32 v35, v35, v174
	v_sub_f32_e32 v51, v51, v174
	v_sub_f32_e32 v36, v36, v174
	v_sub_f32_e32 v52, v52, v174
	v_sub_f32_e32 v37, v37, v174
	v_sub_f32_e32 v53, v53, v174
	v_sub_f32_e32 v38, v38, v174
	v_sub_f32_e32 v54, v54, v174
	v_sub_f32_e32 v39, v39, v174
	v_sub_f32_e32 v55, v55, v174
	v_sub_f32_e32 v40, v40, v174
	v_sub_f32_e32 v56, v56, v174
	v_sub_f32_e32 v41, v41, v174
	v_sub_f32_e32 v57, v57, v174
	v_sub_f32_e32 v42, v42, v174
	v_sub_f32_e32 v58, v58, v174
	v_sub_f32_e32 v43, v43, v174
	v_sub_f32_e32 v59, v59, v174
	v_sub_f32_e32 v44, v44, v174
	v_sub_f32_e32 v60, v60, v174
	v_sub_f32_e32 v45, v45, v174
	v_sub_f32_e32 v61, v61, v174
	v_sub_f32_e32 v46, v46, v174
	v_sub_f32_e32 v62, v62, v174
	v_sub_f32_e32 v47, v47, v174
	v_sub_f32_e32 v63, v63, v174
	v_sub_f32_e32 v64, 0, v174
	v_sub_f32_e32 v65, 0, v174
	v_sub_f32_e32 v66, 0, v174
	v_sub_f32_e32 v67, 0, v174
	v_sub_f32_e32 v68, 0, v174
	v_sub_f32_e32 v69, 0, v174
	v_sub_f32_e32 v70, 0, v174
	v_sub_f32_e32 v71, 0, v174
	v_sub_f32_e32 v72, 0, v174
	v_sub_f32_e32 v73, 0, v174
	v_sub_f32_e32 v74, 0, v174
	v_sub_f32_e32 v75, 0, v174
	v_sub_f32_e32 v76, 0, v174
	v_sub_f32_e32 v77, 0, v174
	v_sub_f32_e32 v78, 0, v174
	v_sub_f32_e32 v79, 0, v174
	s_waitcnt vmcnt(0)
	ds_write_b128 v167, v[120:123] offset:26624
	ds_write_b128 v131, v[124:127] offset:32768
	ds_write_b128 v169, v[132:135] offset:26624
	v_exp_f32_e32 v32, v32
	v_exp_f32_e32 v48, v48
	v_exp_f32_e32 v33, v33
	v_exp_f32_e32 v49, v49
	v_exp_f32_e32 v34, v34
	v_exp_f32_e32 v50, v50
	v_exp_f32_e32 v35, v35
	v_exp_f32_e32 v51, v51
	v_exp_f32_e32 v36, v36
	v_exp_f32_e32 v52, v52
	v_exp_f32_e32 v37, v37
	v_exp_f32_e32 v53, v53
	v_exp_f32_e32 v38, v38
	v_exp_f32_e32 v54, v54
	v_exp_f32_e32 v39, v39
	v_exp_f32_e32 v55, v55
	v_exp_f32_e32 v40, v40
	v_exp_f32_e32 v56, v56
	v_exp_f32_e32 v41, v41
	v_exp_f32_e32 v57, v57
	v_exp_f32_e32 v42, v42
	v_exp_f32_e32 v58, v58
	v_exp_f32_e32 v43, v43
	v_exp_f32_e32 v59, v59
	v_exp_f32_e32 v44, v44
	v_exp_f32_e32 v60, v60
	v_exp_f32_e32 v45, v45
	v_exp_f32_e32 v61, v61
	v_exp_f32_e32 v46, v46
	v_exp_f32_e32 v62, v62
	v_exp_f32_e32 v47, v47
	v_exp_f32_e32 v63, v63
	s_waitcnt lgkmcnt(0)
	global_load_dwordx4 v[120:123], v129, s[4:5]
	global_load_dwordx4 v[124:127], v129, s[4:5] offset:128
	global_load_dwordx4 v[132:135], v130, s[6:7]
	s_add_u32 s4, s4, 0x40000
	s_addc_u32 s5, s5, 0
	s_add_u32 s6, s6, 0x1000
	s_addc_u32 s7, s7, 0
	v_add_f32_e32 v175, v32, v33
	v_add_f32_e32 v174, v48, v49
	v_add_f32_e32 v175, v175, v34
	v_add_f32_e32 v174, v174, v50
	v_add_f32_e32 v175, v175, v35
	v_add_f32_e32 v174, v174, v51
	v_add_f32_e32 v175, v175, v36
	v_add_f32_e32 v174, v174, v52
	v_add_f32_e32 v175, v175, v37
	v_add_f32_e32 v174, v174, v53
	v_add_f32_e32 v175, v175, v38
	v_add_f32_e32 v174, v174, v54
	v_add_f32_e32 v175, v175, v39
	v_add_f32_e32 v174, v174, v55
	v_add_f32_e32 v175, v175, v40
	v_add_f32_e32 v174, v174, v56
	v_add_f32_e32 v175, v175, v41
	v_add_f32_e32 v174, v174, v57
	v_add_f32_e32 v175, v175, v42
	v_add_f32_e32 v174, v174, v58
	v_add_f32_e32 v175, v175, v43
	v_add_f32_e32 v174, v174, v59
	v_add_f32_e32 v175, v175, v44
	v_add_f32_e32 v174, v174, v60
	v_add_f32_e32 v175, v175, v45
	v_add_f32_e32 v174, v174, v61
	v_add_f32_e32 v175, v175, v46
	v_add_f32_e32 v174, v174, v62
	v_add_f32_e32 v175, v175, v47
	v_add_f32_e32 v174, v174, v63
	v_add_f32_e32 v175, v175, v174
	v_add_f32_e32 v173, v173, v175
	v_cvt_pk_bf16_f32 v104, v32, v33
	v_cvt_pk_bf16_f32 v105, v34, v35
	v_cvt_pk_bf16_f32 v106, v36, v37
	v_cvt_pk_bf16_f32 v107, v38, v39
	v_cvt_pk_bf16_f32 v108, v40, v41
	v_cvt_pk_bf16_f32 v109, v42, v43
	v_cvt_pk_bf16_f32 v110, v44, v45
	v_cvt_pk_bf16_f32 v111, v46, v47
	v_cvt_pk_bf16_f32 v112, v48, v49
	v_cvt_pk_bf16_f32 v113, v50, v51
	v_cvt_pk_bf16_f32 v114, v52, v53
	v_cvt_pk_bf16_f32 v115, v54, v55
	v_cvt_pk_bf16_f32 v116, v56, v57
	v_cvt_pk_bf16_f32 v117, v58, v59
	v_cvt_pk_bf16_f32 v118, v60, v61
	v_cvt_pk_bf16_f32 v119, v62, v63
	ds_read_b128 v[184:187], v170 offset:13312
	ds_read_b128 v[188:191], v170 offset:19968
	ds_read_b128 v[192:195], v170 offset:13344
	ds_read_b128 v[196:199], v170 offset:20000
	ds_read_b128 v[200:203], v170 offset:13376
	ds_read_b128 v[204:207], v170 offset:20032
	ds_read_b128 v[208:211], v170 offset:13408
	ds_read_b128 v[212:215], v170 offset:20064
	s_barrier
	s_mov_b32 s13, 32
; __device__ __forceinline__ void at_finishSM(f32x16& p0, f32x16& p1, float alpha, float& l_reg, bf16x8& pa0, bf16x8& pa1, bf16x8& pa2, bf16x8& pa3) {
;     ...
;   l_reg = l_reg * alpha + ps;
;     ...
;   PK4(p0, 0, pa0); PK4(p0, 8, pa1); PK4(p1, 0, pa2); PK4(p1, 8, pa3);
;     ...
; }
; __device__ __forceinline__ void at_qkt(f32x16& p0, f32x16& p1, const char* Ks, const bf16x8* qr, int r32, int hi, float negm) {
; #pragma unroll
;   for (int r = 0; r < 16; ++r) { p0[r] = negm; p1[r] = negm; }
; #pragma unroll
;   for (int d0 = 0; d0 < 6; ++d0) {
;     const bf16x8 b0 = *(const bf16x8*)(Ks + r32 * AT_KROW + d0 * 32 + hi * 16);
;     const bf16x8 b1 = *(const bf16x8*)(Ks + (32 + r32) * AT_KROW + d0 * 32 + hi * 16);
;     p0 = MFMA(b0, qr[d0], p0);
;     p1 = MFMA(b1, qr[d0], p1);
;   }
; }
; __device__ __forceinline__ int v_st(int k, int c) { const int kk = (k & ~0xC) | ((k & 4) << 1) | ((k & 8) >> 1); return ((kk >> 3) * 4 + (c >> 5)) * 512 + ((kk & 7) * 32 + (c & 31)) * 2; }
; __device__ __forceinline__ int v_rd_base(int lane) { return ((lane & 3) << 3) | (((lane >> 2) & 3) << 6) | (((lane >> 4) & 1) << 5) | (((lane >> 5) & 1) << 8); }
; template <int OFF> __device__ __forceinline__ s16x4 tr_read(int vb) {
;   s16x4 r; asm volatile("ds_read_b64_tr_b16 %0, %1 offset:%2" : "=&v"(r) : "v"(vb), "i"(OFF) : "memory"); return r;
; }
; template <int D0> __device__ __forceinline__ void pv_one(f32x16& od, int vb, bf16x8 pa0, bf16x8 pa1, bf16x8 pa2, bf16x8 pa3) {
;   const s16x4 l0 = tr_read<v_rd_off(D0, 0, 0)>(vb), h0 = tr_read<v_rd_off(D0, 0, 1)>(vb), l1 = tr_read<v_rd_off(D0, 1, 0)>(vb), h1 = tr_read<v_rd_off(D0, 1, 1)>(vb);
;   const s16x4 l2 = tr_read<v_rd_off(D0, 2, 0)>(vb), h2 = tr_read<v_rd_off(D0, 2, 1)>(vb), l3 = tr_read<v_rd_off(D0, 3, 0)>(vb), h3 = tr_read<v_rd_off(D0, 3, 1)>(vb);
;   asm volatile("s_waitcnt lgkmcnt(0)" ::: "memory"); SBAR();
;     ...
;   od = MFMA(pa0, PK(l0, h0), od);
;   od = MFMA(pa1, PK(l1, h1), od);
;   od = MFMA(pa2, PK(l2, h2), od);
;   od = MFMA(pa3, PK(l3, h3), od);
;     ...
; }
; __device__ __forceinline__ void pv_d0(f32x16* o, int vb, bf16x8 pa0, bf16x8 pa1, bf16x8 pa2, bf16x8 pa3) {
;   pv_one<0>(o[0], vb, pa0, pa1, pa2, pa3); pv_one<1>(o[1], vb, pa0, pa1, pa2, pa3);
; __device__ void phase_attn(const Params& p, char* lds) {
;     ...
;     for (int j = 1; j + 1 < NT; j += 2) {
;       SBAR(); at_qkt(pB0, pB1, K_lds + AT_SHMK, qr, r32, hi, -m_reg);
.Lat_loop:
	s_waitcnt lgkmcnt(6)
	v_mfma_f32_32x32x16_bf16 v[32:47], v[184:187], v[80:83], v[64:79]
	v_mfma_f32_32x32x16_bf16 v[48:63], v[188:191], v[80:83], v[64:79]
	ds_read_b128 v[184:187], v170 offset:13440
	ds_read_b128 v[188:191], v170 offset:20096
	s_waitcnt lgkmcnt(6)
	v_mfma_f32_32x32x16_bf16 v[32:47], v[192:195], v[84:87], v[32:47]
	v_mfma_f32_32x32x16_bf16 v[48:63], v[196:199], v[84:87], v[48:63]
	ds_read_b128 v[192:195], v170 offset:13472
	ds_read_b128 v[196:199], v170 offset:20128
	s_waitcnt lgkmcnt(6)
	v_mfma_f32_32x32x16_bf16 v[32:47], v[200:203], v[88:91], v[32:47]
	v_mfma_f32_32x32x16_bf16 v[48:63], v[204:207], v[88:91], v[48:63]
	s_waitcnt lgkmcnt(4)
	v_mfma_f32_32x32x16_bf16 v[32:47], v[208:211], v[92:95], v[32:47]
	v_mfma_f32_32x32x16_bf16 v[48:63], v[212:215], v[92:95], v[48:63]
	ds_read_b64_tr_b16 v[148:149], v171 offset:0
	ds_read_b64_tr_b16 v[150:151], v171 offset:2048
	ds_read_b64_tr_b16 v[152:153], v171 offset:4096
	ds_read_b64_tr_b16 v[154:155], v171 offset:6144
	s_waitcnt lgkmcnt(6)
	v_mfma_f32_32x32x16_bf16 v[32:47], v[184:187], v[96:99], v[32:47]
	v_mfma_f32_32x32x16_bf16 v[48:63], v[188:191], v[96:99], v[48:63]
	ds_read_b64_tr_b16 v[156:157], v171 offset:8192
	ds_read_b64_tr_b16 v[158:159], v171 offset:10240
	ds_read_b64_tr_b16 v[216:217], v171 offset:12288
	ds_read_b64_tr_b16 v[218:219], v171 offset:14336
	s_waitcnt lgkmcnt(8)
	v_mfma_f32_32x32x16_bf16 v[32:47], v[192:195], v[100:103], v[32:47]
	v_mfma_f32_32x32x16_bf16 v[48:63], v[196:199], v[100:103], v[48:63]
	ds_read_b64_tr_b16 v[220:221], v171 offset:512
	ds_read_b64_tr_b16 v[222:223], v171 offset:2560
	ds_read_b64_tr_b16 v[224:225], v171 offset:4608
	ds_read_b64_tr_b16 v[226:227], v171 offset:6656
	s_waitcnt lgkmcnt(10)
	v_mfma_f32_32x32x16_bf16 v[0:15], v[104:107], v[148:151], v[0:15]
	s_waitcnt lgkmcnt(8)
	v_mfma_f32_32x32x16_bf16 v[0:15], v[108:111], v[152:155], v[0:15]
	ds_read_b64_tr_b16 v[236:237], v171 offset:8704
	ds_read_b64_tr_b16 v[238:239], v171 offset:10752
	ds_read_b64_tr_b16 v[240:241], v171 offset:12800
	ds_read_b64_tr_b16 v[242:243], v171 offset:14848
	s_waitcnt lgkmcnt(10)
	v_mfma_f32_32x32x16_bf16 v[0:15], v[112:115], v[156:159], v[0:15]
	s_waitcnt lgkmcnt(8)
	v_mfma_f32_32x32x16_bf16 v[0:15], v[116:119], v[216:219], v[0:15]
	s_waitcnt lgkmcnt(6)
	v_mfma_f32_32x32x16_bf16 v[16:31], v[104:107], v[220:223], v[16:31]
	s_waitcnt lgkmcnt(4)
	v_mfma_f32_32x32x16_bf16 v[16:31], v[108:111], v[224:227], v[16:31]
	s_waitcnt lgkmcnt(2)
	v_mfma_f32_32x32x16_bf16 v[16:31], v[112:115], v[236:239], v[16:31]
	s_waitcnt lgkmcnt(0)
	v_mfma_f32_32x32x16_bf16 v[16:31], v[116:119], v[240:243], v[16:31]
	s_barrier
	s_waitcnt vmcnt(0)
	ds_write_b128 v167, v[120:123] offset:39936
	ds_write_b128 v131, v[124:127] offset:49152
	ds_write_b128 v169, v[132:135] offset:39936
	v_exp_f32_e32 v32, v32
	v_exp_f32_e32 v48, v48
	v_exp_f32_e32 v33, v33
	v_exp_f32_e32 v49, v49
	v_exp_f32_e32 v34, v34
	v_exp_f32_e32 v50, v50
	v_exp_f32_e32 v35, v35
	v_exp_f32_e32 v51, v51
	v_exp_f32_e32 v36, v36
	v_exp_f32_e32 v52, v52
	v_exp_f32_e32 v37, v37
	v_exp_f32_e32 v53, v53
	v_exp_f32_e32 v38, v38
	v_exp_f32_e32 v54, v54
	v_exp_f32_e32 v39, v39
	v_exp_f32_e32 v55, v55
	v_exp_f32_e32 v40, v40
	v_exp_f32_e32 v56, v56
	v_exp_f32_e32 v41, v41
	v_exp_f32_e32 v57, v57
	v_exp_f32_e32 v42, v42
	v_exp_f32_e32 v58, v58
	v_exp_f32_e32 v43, v43
	v_exp_f32_e32 v59, v59
	v_exp_f32_e32 v44, v44
	v_exp_f32_e32 v60, v60
	v_exp_f32_e32 v45, v45
	v_exp_f32_e32 v61, v61
	v_exp_f32_e32 v46, v46
	v_exp_f32_e32 v62, v62
	v_exp_f32_e32 v47, v47
	v_exp_f32_e32 v63, v63
	s_waitcnt lgkmcnt(0)
	global_load_dwordx4 v[120:123], v129, s[4:5]
	global_load_dwordx4 v[124:127], v129, s[4:5] offset:128
	global_load_dwordx4 v[132:135], v130, s[6:7]
	s_add_u32 s4, s4, 0x40000
	s_addc_u32 s5, s5, 0
	s_add_u32 s6, s6, 0x1000
	s_addc_u32 s7, s7, 0
	v_add_f32_e32 v175, v32, v33
	v_add_f32_e32 v174, v48, v49
	v_add_f32_e32 v175, v175, v34
	v_add_f32_e32 v174, v174, v50
	v_add_f32_e32 v175, v175, v35
	v_add_f32_e32 v174, v174, v51
	v_add_f32_e32 v175, v175, v36
	v_add_f32_e32 v174, v174, v52
	v_add_f32_e32 v175, v175, v37
	v_add_f32_e32 v174, v174, v53
	v_add_f32_e32 v175, v175, v38
	v_add_f32_e32 v174, v174, v54
	v_add_f32_e32 v175, v175, v39
	v_add_f32_e32 v174, v174, v55
	v_add_f32_e32 v175, v175, v40
	v_add_f32_e32 v174, v174, v56
	v_add_f32_e32 v175, v175, v41
	v_add_f32_e32 v174, v174, v57
	v_add_f32_e32 v175, v175, v42
	v_add_f32_e32 v174, v174, v58
	v_add_f32_e32 v175, v175, v43
	v_add_f32_e32 v174, v174, v59
	v_add_f32_e32 v175, v175, v44
	v_add_f32_e32 v174, v174, v60
	v_add_f32_e32 v175, v175, v45
	v_add_f32_e32 v174, v174, v61
	v_add_f32_e32 v175, v175, v46
	v_add_f32_e32 v174, v174, v62
	v_add_f32_e32 v175, v175, v47
	v_add_f32_e32 v174, v174, v63
	v_add_f32_e32 v175, v175, v174
	v_cmp_ge_f32_e32 vcc, s23, v175
	s_cmp_eq_u64 vcc, exec
	s_cbranch_scc0 .Lat_rare0
; __device__ __forceinline__ void at_qkt(f32x16& p0, f32x16& p1, const char* Ks, const bf16x8* qr, int r32, int hi, float negm) {
; #pragma unroll
;   for (int r = 0; r < 16; ++r) { p0[r] = negm; p1[r] = negm; }
; #pragma unroll
;   for (int d0 = 0; d0 < 6; ++d0) {
;     const bf16x8 b0 = *(const bf16x8*)(Ks + r32 * AT_KROW + d0 * 32 + hi * 16);
;     const bf16x8 b1 = *(const bf16x8*)(Ks + (32 + r32) * AT_KROW + d0 * 32 + hi * 16);
;     p0 = MFMA(b0, qr[d0], p0);
;     p1 = MFMA(b1, qr[d0], p1);
;   }
; }
; __device__ __forceinline__ int v_st(int k, int c) { const int kk = (k & ~0xC) | ((k & 4) << 1) | ((k & 8) >> 1); return ((kk >> 3) * 4 + (c >> 5)) * 512 + ((kk & 7) * 32 + (c & 31)) * 2; }
; __device__ __forceinline__ int v_rd_base(int lane) { return ((lane & 3) << 3) | (((lane >> 2) & 3) << 6) | (((lane >> 4) & 1) << 5) | (((lane >> 5) & 1) << 8); }
; template <int OFF> __device__ __forceinline__ s16x4 tr_read(int vb) {
;   s16x4 r; asm volatile("ds_read_b64_tr_b16 %0, %1 offset:%2" : "=&v"(r) : "v"(vb), "i"(OFF) : "memory"); return r;
; }
; template <int D0> __device__ __forceinline__ void pv_one(f32x16& od, int vb, bf16x8 pa0, bf16x8 pa1, bf16x8 pa2, bf16x8 pa3) {
;   const s16x4 l0 = tr_read<v_rd_off(D0, 0, 0)>(vb), h0 = tr_read<v_rd_off(D0, 0, 1)>(vb), l1 = tr_read<v_rd_off(D0, 1, 0)>(vb), h1 = tr_read<v_rd_off(D0, 1, 1)>(vb);
;   const s16x4 l2 = tr_read<v_rd_off(D0, 2, 0)>(vb), h2 = tr_read<v_rd_off(D0, 2, 1)>(vb), l3 = tr_read<v_rd_off(D0, 3, 0)>(vb), h3 = tr_read<v_rd_off(D0, 3, 1)>(vb);
;   asm volatile("s_waitcnt lgkmcnt(0)" ::: "memory"); SBAR();
;     ...
;   od = MFMA(pa0, PK(l0, h0), od);
;   od = MFMA(pa1, PK(l1, h1), od);
;   od = MFMA(pa2, PK(l2, h2), od);
;   od = MFMA(pa3, PK(l3, h3), od);
;     ...
; }
; __device__ __forceinline__ void pv_d0(f32x16* o, int vb, bf16x8 pa0, bf16x8 pa1, bf16x8 pa2, bf16x8 pa3) {
;   pv_one<0>(o[0], vb, pa0, pa1, pa2, pa3); pv_one<1>(o[1], vb, pa0, pa1, pa2, pa3);
; __device__ void phase_attn(const Params& p, char* lds) {
;     ...
;     for (int j = 1; j + 1 < NT; j += 2) {
;       SBAR(); at_qkt(pB0, pB1, K_lds + AT_SHMK, qr, r32, hi, -m_reg);
;       at_finishSM(pA0, pA1, alA, l_reg, pa0, pa1, pa2, pa3); SBAR();
;       SLOAD(1, (j + 2) * 64); SBAR();
;       pv_d0(o, vb0, pa0, pa1, pa2, pa3); at_partialSM(pB0, pB1, m_reg, alB, false);
;       __syncthreads(); SWAIT(); SWRITE(0, 0);
;       RESC(alB); __syncthreads();
.Lat_rare0_back:
	v_add_f32_e32 v173, v173, v175
	v_cvt_pk_bf16_f32 v104, v32, v33
	v_cvt_pk_bf16_f32 v105, v34, v35
	v_cvt_pk_bf16_f32 v106, v36, v37
	v_cvt_pk_bf16_f32 v107, v38, v39
	v_cvt_pk_bf16_f32 v108, v40, v41
	v_cvt_pk_bf16_f32 v109, v42, v43
	v_cvt_pk_bf16_f32 v110, v44, v45
	v_cvt_pk_bf16_f32 v111, v46, v47
	v_cvt_pk_bf16_f32 v112, v48, v49
	v_cvt_pk_bf16_f32 v113, v50, v51
	v_cvt_pk_bf16_f32 v114, v52, v53
	v_cvt_pk_bf16_f32 v115, v54, v55
	v_cvt_pk_bf16_f32 v116, v56, v57
	v_cvt_pk_bf16_f32 v117, v58, v59
	v_cvt_pk_bf16_f32 v118, v60, v61
	v_cvt_pk_bf16_f32 v119, v62, v63
	ds_read_b128 v[184:187], v170 offset:26624
	ds_read_b128 v[188:191], v170 offset:33280
	ds_read_b128 v[192:195], v170 offset:26656
	ds_read_b128 v[196:199], v170 offset:33312
	ds_read_b128 v[200:203], v170 offset:26688
	ds_read_b128 v[204:207], v170 offset:33344
	ds_read_b128 v[208:211], v170 offset:26720
	ds_read_b128 v[212:215], v170 offset:33376
	s_barrier
	s_waitcnt lgkmcnt(6)
	v_mfma_f32_32x32x16_bf16 v[32:47], v[184:187], v[80:83], v[64:79]
	v_mfma_f32_32x32x16_bf16 v[48:63], v[188:191], v[80:83], v[64:79]
	ds_read_b128 v[184:187], v170 offset:26752
	ds_read_b128 v[188:191], v170 offset:33408
	s_waitcnt lgkmcnt(6)
	v_mfma_f32_32x32x16_bf16 v[32:47], v[192:195], v[84:87], v[32:47]
	v_mfma_f32_32x32x16_bf16 v[48:63], v[196:199], v[84:87], v[48:63]
	ds_read_b128 v[192:195], v170 offset:26784
	ds_read_b128 v[196:199], v170 offset:33440
	s_waitcnt lgkmcnt(6)
	v_mfma_f32_32x32x16_bf16 v[32:47], v[200:203], v[88:91], v[32:47]
	v_mfma_f32_32x32x16_bf16 v[48:63], v[204:207], v[88:91], v[48:63]
	s_waitcnt lgkmcnt(4)
	v_mfma_f32_32x32x16_bf16 v[32:47], v[208:211], v[92:95], v[32:47]
	v_mfma_f32_32x32x16_bf16 v[48:63], v[212:215], v[92:95], v[48:63]
	ds_read_b64_tr_b16 v[148:149], v171 offset:16384
	ds_read_b64_tr_b16 v[150:151], v171 offset:18432
	ds_read_b64_tr_b16 v[152:153], v171 offset:20480
	ds_read_b64_tr_b16 v[154:155], v171 offset:22528
	s_waitcnt lgkmcnt(6)
	v_mfma_f32_32x32x16_bf16 v[32:47], v[184:187], v[96:99], v[32:47]
	v_mfma_f32_32x32x16_bf16 v[48:63], v[188:191], v[96:99], v[48:63]
	ds_read_b64_tr_b16 v[156:157], v171 offset:24576
	ds_read_b64_tr_b16 v[158:159], v171 offset:26624
	ds_read_b64_tr_b16 v[216:217], v171 offset:28672
	ds_read_b64_tr_b16 v[218:219], v171 offset:30720
	s_waitcnt lgkmcnt(8)
	v_mfma_f32_32x32x16_bf16 v[32:47], v[192:195], v[100:103], v[32:47]
	v_mfma_f32_32x32x16_bf16 v[48:63], v[196:199], v[100:103], v[48:63]
	ds_read_b64_tr_b16 v[220:221], v171 offset:16896
	ds_read_b64_tr_b16 v[222:223], v171 offset:18944
	ds_read_b64_tr_b16 v[224:225], v171 offset:20992
	ds_read_b64_tr_b16 v[226:227], v171 offset:23040
	s_waitcnt lgkmcnt(10)
	v_mfma_f32_32x32x16_bf16 v[0:15], v[104:107], v[148:151], v[0:15]
	s_waitcnt lgkmcnt(8)
	v_mfma_f32_32x32x16_bf16 v[0:15], v[108:111], v[152:155], v[0:15]
	ds_read_b64_tr_b16 v[236:237], v171 offset:25088
	ds_read_b64_tr_b16 v[238:239], v171 offset:27136
	ds_read_b64_tr_b16 v[240:241], v171 offset:29184
	ds_read_b64_tr_b16 v[242:243], v171 offset:31232
	s_waitcnt lgkmcnt(10)
	v_mfma_f32_32x32x16_bf16 v[0:15], v[112:115], v[156:159], v[0:15]
	s_waitcnt lgkmcnt(8)
	v_mfma_f32_32x32x16_bf16 v[0:15], v[116:119], v[216:219], v[0:15]
	s_waitcnt lgkmcnt(6)
	v_mfma_f32_32x32x16_bf16 v[16:31], v[104:107], v[220:223], v[16:31]
	s_waitcnt lgkmcnt(4)
	v_mfma_f32_32x32x16_bf16 v[16:31], v[108:111], v[224:227], v[16:31]
	s_waitcnt lgkmcnt(2)
	v_mfma_f32_32x32x16_bf16 v[16:31], v[112:115], v[236:239], v[16:31]
	s_waitcnt lgkmcnt(0)
	v_mfma_f32_32x32x16_bf16 v[16:31], v[116:119], v[240:243], v[16:31]
	s_barrier
	s_waitcnt vmcnt(0)
	ds_write_b128 v167, v[120:123] offset:0
	ds_write_b128 v131, v[124:127] offset:0
	ds_write_b128 v169, v[132:135] offset:0
	v_exp_f32_e32 v32, v32
	v_exp_f32_e32 v48, v48
	v_exp_f32_e32 v33, v33
	v_exp_f32_e32 v49, v49
	v_exp_f32_e32 v34, v34
	v_exp_f32_e32 v50, v50
	v_exp_f32_e32 v35, v35
	v_exp_f32_e32 v51, v51
	v_exp_f32_e32 v36, v36
	v_exp_f32_e32 v52, v52
	v_exp_f32_e32 v37, v37
	v_exp_f32_e32 v53, v53
	v_exp_f32_e32 v38, v38
	v_exp_f32_e32 v54, v54
	v_exp_f32_e32 v39, v39
	v_exp_f32_e32 v55, v55
	v_exp_f32_e32 v40, v40
	v_exp_f32_e32 v56, v56
	v_exp_f32_e32 v41, v41
	v_exp_f32_e32 v57, v57
	v_exp_f32_e32 v42, v42
	v_exp_f32_e32 v58, v58
	v_exp_f32_e32 v43, v43
	v_exp_f32_e32 v59, v59
	v_exp_f32_e32 v44, v44
	v_exp_f32_e32 v60, v60
	v_exp_f32_e32 v45, v45
	v_exp_f32_e32 v61, v61
	v_exp_f32_e32 v46, v46
	v_exp_f32_e32 v62, v62
	v_exp_f32_e32 v47, v47
	v_exp_f32_e32 v63, v63
	s_waitcnt lgkmcnt(0)
	global_load_dwordx4 v[120:123], v129, s[4:5]
	global_load_dwordx4 v[124:127], v129, s[4:5] offset:128
	global_load_dwordx4 v[132:135], v130, s[6:7]
	s_add_u32 s4, s4, 0x40000
	s_addc_u32 s5, s5, 0
	s_add_u32 s6, s6, 0x1000
	s_addc_u32 s7, s7, 0
	v_add_f32_e32 v175, v32, v33
	v_add_f32_e32 v174, v48, v49
	v_add_f32_e32 v175, v175, v34
	v_add_f32_e32 v174, v174, v50
	v_add_f32_e32 v175, v175, v35
	v_add_f32_e32 v174, v174, v51
	v_add_f32_e32 v175, v175, v36
	v_add_f32_e32 v174, v174, v52
	v_add_f32_e32 v175, v175, v37
	v_add_f32_e32 v174, v174, v53
	v_add_f32_e32 v175, v175, v38
	v_add_f32_e32 v174, v174, v54
	v_add_f32_e32 v175, v175, v39
	v_add_f32_e32 v174, v174, v55
	v_add_f32_e32 v175, v175, v40
	v_add_f32_e32 v174, v174, v56
	v_add_f32_e32 v175, v175, v41
	v_add_f32_e32 v174, v174, v57
	v_add_f32_e32 v175, v175, v42
	v_add_f32_e32 v174, v174, v58
	v_add_f32_e32 v175, v175, v43
	v_add_f32_e32 v174, v174, v59
	v_add_f32_e32 v175, v175, v44
	v_add_f32_e32 v174, v174, v60
	v_add_f32_e32 v175, v175, v45
	v_add_f32_e32 v174, v174, v61
	v_add_f32_e32 v175, v175, v46
	v_add_f32_e32 v174, v174, v62
	v_add_f32_e32 v175, v175, v47
	v_add_f32_e32 v174, v174, v63
	v_add_f32_e32 v175, v175, v174
	v_cmp_ge_f32_e32 vcc, s23, v175
	s_cmp_eq_u64 vcc, exec
	s_cbranch_scc0 .Lat_rare1
; __device__ __forceinline__ void at_qkt(f32x16& p0, f32x16& p1, const char* Ks, const bf16x8* qr, int r32, int hi, float negm) {
; #pragma unroll
;   for (int r = 0; r < 16; ++r) { p0[r] = negm; p1[r] = negm; }
; #pragma unroll
;   for (int d0 = 0; d0 < 6; ++d0) {
;     const bf16x8 b0 = *(const bf16x8*)(Ks + r32 * AT_KROW + d0 * 32 + hi * 16);
;     const bf16x8 b1 = *(const bf16x8*)(Ks + (32 + r32) * AT_KROW + d0 * 32 + hi * 16);
;     p0 = MFMA(b0, qr[d0], p0);
;     p1 = MFMA(b1, qr[d0], p1);
;   }
; }
; __device__ __forceinline__ int v_st(int k, int c) { const int kk = (k & ~0xC) | ((k & 4) << 1) | ((k & 8) >> 1); return ((kk >> 3) * 4 + (c >> 5)) * 512 + ((kk & 7) * 32 + (c & 31)) * 2; }
; __device__ __forceinline__ int v_rd_base(int lane) { return ((lane & 3) << 3) | (((lane >> 2) & 3) << 6) | (((lane >> 4) & 1) << 5) | (((lane >> 5) & 1) << 8); }
; template <int OFF> __device__ __forceinline__ s16x4 tr_read(int vb) {
;   s16x4 r; asm volatile("ds_read_b64_tr_b16 %0, %1 offset:%2" : "=&v"(r) : "v"(vb), "i"(OFF) : "memory"); return r;
; }
; template <int D0> __device__ __forceinline__ void pv_one(f32x16& od, int vb, bf16x8 pa0, bf16x8 pa1, bf16x8 pa2, bf16x8 pa3) {
;   const s16x4 l0 = tr_read<v_rd_off(D0, 0, 0)>(vb), h0 = tr_read<v_rd_off(D0, 0, 1)>(vb), l1 = tr_read<v_rd_off(D0, 1, 0)>(vb), h1 = tr_read<v_rd_off(D0, 1, 1)>(vb);
;   const s16x4 l2 = tr_read<v_rd_off(D0, 2, 0)>(vb), h2 = tr_read<v_rd_off(D0, 2, 1)>(vb), l3 = tr_read<v_rd_off(D0, 3, 0)>(vb), h3 = tr_read<v_rd_off(D0, 3, 1)>(vb);
;   asm volatile("s_waitcnt lgkmcnt(0)" ::: "memory"); SBAR();
;     ...
;   od = MFMA(pa0, PK(l0, h0), od);
;   od = MFMA(pa1, PK(l1, h1), od);
;   od = MFMA(pa2, PK(l2, h2), od);
;   od = MFMA(pa3, PK(l3, h3), od);
;     ...
; }
; __device__ __forceinline__ void pv_d0(f32x16* o, int vb, bf16x8 pa0, bf16x8 pa1, bf16x8 pa2, bf16x8 pa3) {
;   pv_one<0>(o[0], vb, pa0, pa1, pa2, pa3); pv_one<1>(o[1], vb, pa0, pa1, pa2, pa3);
; __device__ void phase_attn(const Params& p, char* lds) {
;     ...
;     for (int j = 1; j + 1 < NT; j += 2) {
;       SBAR(); at_qkt(pB0, pB1, K_lds + AT_SHMK, qr, r32, hi, -m_reg);
;       at_finishSM(pA0, pA1, alA, l_reg, pa0, pa1, pa2, pa3); SBAR();
;       SLOAD(1, (j + 2) * 64); SBAR();
;       pv_d0(o, vb0, pa0, pa1, pa2, pa3); at_partialSM(pB0, pB1, m_reg, alB, false);
;       __syncthreads(); SWAIT(); SWRITE(0, 0);
;       RESC(alB); __syncthreads();
.Lat_rare1_back:
	v_add_f32_e32 v173, v173, v175
	v_cvt_pk_bf16_f32 v104, v32, v33
	v_cvt_pk_bf16_f32 v105, v34, v35
	v_cvt_pk_bf16_f32 v106, v36, v37
	v_cvt_pk_bf16_f32 v107, v38, v39
	v_cvt_pk_bf16_f32 v108, v40, v41
	v_cvt_pk_bf16_f32 v109, v42, v43
	v_cvt_pk_bf16_f32 v110, v44, v45
	v_cvt_pk_bf16_f32 v111, v46, v47
	v_cvt_pk_bf16_f32 v112, v48, v49
	v_cvt_pk_bf16_f32 v113, v50, v51
	v_cvt_pk_bf16_f32 v114, v52, v53
	v_cvt_pk_bf16_f32 v115, v54, v55
	v_cvt_pk_bf16_f32 v116, v56, v57
	v_cvt_pk_bf16_f32 v117, v58, v59
	v_cvt_pk_bf16_f32 v118, v60, v61
	v_cvt_pk_bf16_f32 v119, v62, v63
	ds_read_b128 v[184:187], v170 offset:39936
	ds_read_b128 v[188:191], v170 offset:46592
	ds_read_b128 v[192:195], v170 offset:39968
	ds_read_b128 v[196:199], v170 offset:46624
	ds_read_b128 v[200:203], v170 offset:40000
	ds_read_b128 v[204:207], v170 offset:46656
	ds_read_b128 v[208:211], v170 offset:40032
	ds_read_b128 v[212:215], v170 offset:46688
	s_barrier
	s_waitcnt lgkmcnt(6)
	v_mfma_f32_32x32x16_bf16 v[32:47], v[184:187], v[80:83], v[64:79]
	v_mfma_f32_32x32x16_bf16 v[48:63], v[188:191], v[80:83], v[64:79]
	ds_read_b128 v[184:187], v170 offset:40064
	ds_read_b128 v[188:191], v170 offset:46720
	s_waitcnt lgkmcnt(6)
	v_mfma_f32_32x32x16_bf16 v[32:47], v[192:195], v[84:87], v[32:47]
	v_mfma_f32_32x32x16_bf16 v[48:63], v[196:199], v[84:87], v[48:63]
	ds_read_b128 v[192:195], v170 offset:40096
	ds_read_b128 v[196:199], v170 offset:46752
	s_waitcnt lgkmcnt(6)
	v_mfma_f32_32x32x16_bf16 v[32:47], v[200:203], v[88:91], v[32:47]
	v_mfma_f32_32x32x16_bf16 v[48:63], v[204:207], v[88:91], v[48:63]
	s_waitcnt lgkmcnt(4)
	v_mfma_f32_32x32x16_bf16 v[32:47], v[208:211], v[92:95], v[32:47]
	v_mfma_f32_32x32x16_bf16 v[48:63], v[212:215], v[92:95], v[48:63]
	ds_read_b64_tr_b16 v[148:149], v171 offset:32768
	ds_read_b64_tr_b16 v[150:151], v171 offset:34816
	ds_read_b64_tr_b16 v[152:153], v171 offset:36864
	ds_read_b64_tr_b16 v[154:155], v171 offset:38912
	s_waitcnt lgkmcnt(6)
	v_mfma_f32_32x32x16_bf16 v[32:47], v[184:187], v[96:99], v[32:47]
	v_mfma_f32_32x32x16_bf16 v[48:63], v[188:191], v[96:99], v[48:63]
	ds_read_b64_tr_b16 v[156:157], v171 offset:40960
	ds_read_b64_tr_b16 v[158:159], v171 offset:43008
	ds_read_b64_tr_b16 v[216:217], v171 offset:45056
	ds_read_b64_tr_b16 v[218:219], v171 offset:47104
	s_waitcnt lgkmcnt(8)
	v_mfma_f32_32x32x16_bf16 v[32:47], v[192:195], v[100:103], v[32:47]
	v_mfma_f32_32x32x16_bf16 v[48:63], v[196:199], v[100:103], v[48:63]
	ds_read_b64_tr_b16 v[220:221], v171 offset:33280
	ds_read_b64_tr_b16 v[222:223], v171 offset:35328
	ds_read_b64_tr_b16 v[224:225], v171 offset:37376
	ds_read_b64_tr_b16 v[226:227], v171 offset:39424
	s_waitcnt lgkmcnt(10)
	v_mfma_f32_32x32x16_bf16 v[0:15], v[104:107], v[148:151], v[0:15]
	s_waitcnt lgkmcnt(8)
	v_mfma_f32_32x32x16_bf16 v[0:15], v[108:111], v[152:155], v[0:15]
	ds_read_b64_tr_b16 v[236:237], v171 offset:41472
	ds_read_b64_tr_b16 v[238:239], v171 offset:43520
	ds_read_b64_tr_b16 v[240:241], v171 offset:45568
	ds_read_b64_tr_b16 v[242:243], v171 offset:47616
	s_waitcnt lgkmcnt(10)
	v_mfma_f32_32x32x16_bf16 v[0:15], v[112:115], v[156:159], v[0:15]
	s_waitcnt lgkmcnt(8)
	v_mfma_f32_32x32x16_bf16 v[0:15], v[116:119], v[216:219], v[0:15]
	s_waitcnt lgkmcnt(6)
	v_mfma_f32_32x32x16_bf16 v[16:31], v[104:107], v[220:223], v[16:31]
	s_waitcnt lgkmcnt(4)
	v_mfma_f32_32x32x16_bf16 v[16:31], v[108:111], v[224:227], v[16:31]
	s_waitcnt lgkmcnt(2)
	v_mfma_f32_32x32x16_bf16 v[16:31], v[112:115], v[236:239], v[16:31]
	s_waitcnt lgkmcnt(0)
	v_mfma_f32_32x32x16_bf16 v[16:31], v[116:119], v[240:243], v[16:31]
	s_barrier
	s_waitcnt vmcnt(0)
	ds_write_b128 v167, v[120:123] offset:13312
	ds_write_b128 v131, v[124:127] offset:16384
	ds_write_b128 v169, v[132:135] offset:13312
	v_exp_f32_e32 v32, v32
	v_exp_f32_e32 v48, v48
	v_exp_f32_e32 v33, v33
	v_exp_f32_e32 v49, v49
	v_exp_f32_e32 v34, v34
	v_exp_f32_e32 v50, v50
	v_exp_f32_e32 v35, v35
	v_exp_f32_e32 v51, v51
	v_exp_f32_e32 v36, v36
	v_exp_f32_e32 v52, v52
	v_exp_f32_e32 v37, v37
	v_exp_f32_e32 v53, v53
	v_exp_f32_e32 v38, v38
	v_exp_f32_e32 v54, v54
	v_exp_f32_e32 v39, v39
	v_exp_f32_e32 v55, v55
	v_exp_f32_e32 v40, v40
	v_exp_f32_e32 v56, v56
	v_exp_f32_e32 v41, v41
	v_exp_f32_e32 v57, v57
	v_exp_f32_e32 v42, v42
	v_exp_f32_e32 v58, v58
	v_exp_f32_e32 v43, v43
	v_exp_f32_e32 v59, v59
	v_exp_f32_e32 v44, v44
	v_exp_f32_e32 v60, v60
	v_exp_f32_e32 v45, v45
	v_exp_f32_e32 v61, v61
	v_exp_f32_e32 v46, v46
	v_exp_f32_e32 v62, v62
	v_exp_f32_e32 v47, v47
	v_exp_f32_e32 v63, v63
	s_waitcnt lgkmcnt(0)
	global_load_dwordx4 v[120:123], v129, s[4:5]
	global_load_dwordx4 v[124:127], v129, s[4:5] offset:128
	global_load_dwordx4 v[132:135], v130, s[6:7]
	s_add_u32 s4, s4, 0x40000
	s_addc_u32 s5, s5, 0
	s_add_u32 s6, s6, 0x1000
	s_addc_u32 s7, s7, 0
	v_add_f32_e32 v175, v32, v33
	v_add_f32_e32 v174, v48, v49
	v_add_f32_e32 v175, v175, v34
	v_add_f32_e32 v174, v174, v50
	v_add_f32_e32 v175, v175, v35
	v_add_f32_e32 v174, v174, v51
	v_add_f32_e32 v175, v175, v36
	v_add_f32_e32 v174, v174, v52
	v_add_f32_e32 v175, v175, v37
	v_add_f32_e32 v174, v174, v53
	v_add_f32_e32 v175, v175, v38
	v_add_f32_e32 v174, v174, v54
	v_add_f32_e32 v175, v175, v39
	v_add_f32_e32 v174, v174, v55
	v_add_f32_e32 v175, v175, v40
	v_add_f32_e32 v174, v174, v56
	v_add_f32_e32 v175, v175, v41
	v_add_f32_e32 v174, v174, v57
	v_add_f32_e32 v175, v175, v42
	v_add_f32_e32 v174, v174, v58
	v_add_f32_e32 v175, v175, v43
	v_add_f32_e32 v174, v174, v59
	v_add_f32_e32 v175, v175, v44
	v_add_f32_e32 v174, v174, v60
	v_add_f32_e32 v175, v175, v45
	v_add_f32_e32 v174, v174, v61
	v_add_f32_e32 v175, v175, v46
	v_add_f32_e32 v174, v174, v62
	v_add_f32_e32 v175, v175, v47
	v_add_f32_e32 v174, v174, v63
	v_add_f32_e32 v175, v175, v174
	v_cmp_ge_f32_e32 vcc, s23, v175
	s_cmp_eq_u64 vcc, exec
	s_cbranch_scc0 .Lat_rare2
; __device__ __forceinline__ void at_qkt(f32x16& p0, f32x16& p1, const char* Ks, const bf16x8* qr, int r32, int hi, float negm) {
; #pragma unroll
;   for (int r = 0; r < 16; ++r) { p0[r] = negm; p1[r] = negm; }
; #pragma unroll
;   for (int d0 = 0; d0 < 6; ++d0) {
;     const bf16x8 b0 = *(const bf16x8*)(Ks + r32 * AT_KROW + d0 * 32 + hi * 16);
;     const bf16x8 b1 = *(const bf16x8*)(Ks + (32 + r32) * AT_KROW + d0 * 32 + hi * 16);
;     p0 = MFMA(b0, qr[d0], p0);
;     p1 = MFMA(b1, qr[d0], p1);
;   }
; }
; __device__ __forceinline__ int v_st(int k, int c) { const int kk = (k & ~0xC) | ((k & 4) << 1) | ((k & 8) >> 1); return ((kk >> 3) * 4 + (c >> 5)) * 512 + ((kk & 7) * 32 + (c & 31)) * 2; }
; __device__ __forceinline__ int v_rd_base(int lane) { return ((lane & 3) << 3) | (((lane >> 2) & 3) << 6) | (((lane >> 4) & 1) << 5) | (((lane >> 5) & 1) << 8); }
; template <int OFF> __device__ __forceinline__ s16x4 tr_read(int vb) {
;   s16x4 r; asm volatile("ds_read_b64_tr_b16 %0, %1 offset:%2" : "=&v"(r) : "v"(vb), "i"(OFF) : "memory"); return r;
; }
; template <int D0> __device__ __forceinline__ void pv_one(f32x16& od, int vb, bf16x8 pa0, bf16x8 pa1, bf16x8 pa2, bf16x8 pa3) {
;   const s16x4 l0 = tr_read<v_rd_off(D0, 0, 0)>(vb), h0 = tr_read<v_rd_off(D0, 0, 1)>(vb), l1 = tr_read<v_rd_off(D0, 1, 0)>(vb), h1 = tr_read<v_rd_off(D0, 1, 1)>(vb);
;   const s16x4 l2 = tr_read<v_rd_off(D0, 2, 0)>(vb), h2 = tr_read<v_rd_off(D0, 2, 1)>(vb), l3 = tr_read<v_rd_off(D0, 3, 0)>(vb), h3 = tr_read<v_rd_off(D0, 3, 1)>(vb);
;   asm volatile("s_waitcnt lgkmcnt(0)" ::: "memory"); SBAR();
;     ...
;   od = MFMA(pa0, PK(l0, h0), od);
;   od = MFMA(pa1, PK(l1, h1), od);
;   od = MFMA(pa2, PK(l2, h2), od);
;   od = MFMA(pa3, PK(l3, h3), od);
;     ...
; }
; __device__ __forceinline__ void pv_d0(f32x16* o, int vb, bf16x8 pa0, bf16x8 pa1, bf16x8 pa2, bf16x8 pa3) {
;   pv_one<0>(o[0], vb, pa0, pa1, pa2, pa3); pv_one<1>(o[1], vb, pa0, pa1, pa2, pa3);
; __device__ void phase_attn(const Params& p, char* lds) {
;     ...
;     for (int j = 1; j + 1 < NT; j += 2) {
;       SBAR(); at_qkt(pB0, pB1, K_lds + AT_SHMK, qr, r32, hi, -m_reg);
;       at_finishSM(pA0, pA1, alA, l_reg, pa0, pa1, pa2, pa3); SBAR();
;       SLOAD(1, (j + 2) * 64); SBAR();
;       pv_d0(o, vb0, pa0, pa1, pa2, pa3); at_partialSM(pB0, pB1, m_reg, alB, false);
;       __syncthreads(); SWAIT(); SWRITE(0, 0);
;       RESC(alB); __syncthreads();
.Lat_rare2_back:
	v_add_f32_e32 v173, v173, v175
	v_cvt_pk_bf16_f32 v104, v32, v33
	v_cvt_pk_bf16_f32 v105, v34, v35
	v_cvt_pk_bf16_f32 v106, v36, v37
	v_cvt_pk_bf16_f32 v107, v38, v39
	v_cvt_pk_bf16_f32 v108, v40, v41
	v_cvt_pk_bf16_f32 v109, v42, v43
	v_cvt_pk_bf16_f32 v110, v44, v45
	v_cvt_pk_bf16_f32 v111, v46, v47
	v_cvt_pk_bf16_f32 v112, v48, v49
	v_cvt_pk_bf16_f32 v113, v50, v51
	v_cvt_pk_bf16_f32 v114, v52, v53
	v_cvt_pk_bf16_f32 v115, v54, v55
	v_cvt_pk_bf16_f32 v116, v56, v57
	v_cvt_pk_bf16_f32 v117, v58, v59
	v_cvt_pk_bf16_f32 v118, v60, v61
	v_cvt_pk_bf16_f32 v119, v62, v63
	ds_read_b128 v[184:187], v170 offset:0
	ds_read_b128 v[188:191], v170 offset:6656
	ds_read_b128 v[192:195], v170 offset:32
	ds_read_b128 v[196:199], v170 offset:6688
	ds_read_b128 v[200:203], v170 offset:64
	ds_read_b128 v[204:207], v170 offset:6720
	ds_read_b128 v[208:211], v170 offset:96
	ds_read_b128 v[212:215], v170 offset:6752
	s_barrier
	s_waitcnt lgkmcnt(6)
	v_mfma_f32_32x32x16_bf16 v[32:47], v[184:187], v[80:83], v[64:79]
	v_mfma_f32_32x32x16_bf16 v[48:63], v[188:191], v[80:83], v[64:79]
	ds_read_b128 v[184:187], v170 offset:128
	ds_read_b128 v[188:191], v170 offset:6784
	s_waitcnt lgkmcnt(6)
	v_mfma_f32_32x32x16_bf16 v[32:47], v[192:195], v[84:87], v[32:47]
	v_mfma_f32_32x32x16_bf16 v[48:63], v[196:199], v[84:87], v[48:63]
	ds_read_b128 v[192:195], v170 offset:160
	ds_read_b128 v[196:199], v170 offset:6816
	s_waitcnt lgkmcnt(6)
	v_mfma_f32_32x32x16_bf16 v[32:47], v[200:203], v[88:91], v[32:47]
	v_mfma_f32_32x32x16_bf16 v[48:63], v[204:207], v[88:91], v[48:63]
	s_waitcnt lgkmcnt(4)
	v_mfma_f32_32x32x16_bf16 v[32:47], v[208:211], v[92:95], v[32:47]
	v_mfma_f32_32x32x16_bf16 v[48:63], v[212:215], v[92:95], v[48:63]
	ds_read_b64_tr_b16 v[148:149], v171 offset:49152
	ds_read_b64_tr_b16 v[150:151], v171 offset:51200
	ds_read_b64_tr_b16 v[152:153], v171 offset:53248
	ds_read_b64_tr_b16 v[154:155], v171 offset:55296
	s_waitcnt lgkmcnt(6)
	v_mfma_f32_32x32x16_bf16 v[32:47], v[184:187], v[96:99], v[32:47]
	v_mfma_f32_32x32x16_bf16 v[48:63], v[188:191], v[96:99], v[48:63]
	ds_read_b64_tr_b16 v[156:157], v171 offset:57344
	ds_read_b64_tr_b16 v[158:159], v171 offset:59392
	ds_read_b64_tr_b16 v[216:217], v171 offset:61440
	ds_read_b64_tr_b16 v[218:219], v171 offset:63488
	s_waitcnt lgkmcnt(8)
	v_mfma_f32_32x32x16_bf16 v[32:47], v[192:195], v[100:103], v[32:47]
	v_mfma_f32_32x32x16_bf16 v[48:63], v[196:199], v[100:103], v[48:63]
	ds_read_b64_tr_b16 v[220:221], v171 offset:49664
	ds_read_b64_tr_b16 v[222:223], v171 offset:51712
	ds_read_b64_tr_b16 v[224:225], v171 offset:53760
	ds_read_b64_tr_b16 v[226:227], v171 offset:55808
	s_waitcnt lgkmcnt(10)
	v_mfma_f32_32x32x16_bf16 v[0:15], v[104:107], v[148:151], v[0:15]
	s_waitcnt lgkmcnt(8)
	v_mfma_f32_32x32x16_bf16 v[0:15], v[108:111], v[152:155], v[0:15]
	ds_read_b64_tr_b16 v[236:237], v171 offset:57856
	ds_read_b64_tr_b16 v[238:239], v171 offset:59904
	ds_read_b64_tr_b16 v[240:241], v171 offset:61952
	ds_read_b64_tr_b16 v[242:243], v171 offset:64000
	s_waitcnt lgkmcnt(10)
	v_mfma_f32_32x32x16_bf16 v[0:15], v[112:115], v[156:159], v[0:15]
	s_waitcnt lgkmcnt(8)
	v_mfma_f32_32x32x16_bf16 v[0:15], v[116:119], v[216:219], v[0:15]
	s_waitcnt lgkmcnt(6)
	v_mfma_f32_32x32x16_bf16 v[16:31], v[104:107], v[220:223], v[16:31]
	s_waitcnt lgkmcnt(4)
	v_mfma_f32_32x32x16_bf16 v[16:31], v[108:111], v[224:227], v[16:31]
	s_waitcnt lgkmcnt(2)
	v_mfma_f32_32x32x16_bf16 v[16:31], v[112:115], v[236:239], v[16:31]
	s_waitcnt lgkmcnt(0)
	v_mfma_f32_32x32x16_bf16 v[16:31], v[116:119], v[240:243], v[16:31]
	s_barrier
	s_waitcnt vmcnt(0)
	ds_write_b128 v167, v[120:123] offset:26624
	ds_write_b128 v131, v[124:127] offset:32768
	ds_write_b128 v169, v[132:135] offset:26624
	v_exp_f32_e32 v32, v32
	v_exp_f32_e32 v48, v48
	v_exp_f32_e32 v33, v33
	v_exp_f32_e32 v49, v49
	v_exp_f32_e32 v34, v34
	v_exp_f32_e32 v50, v50
	v_exp_f32_e32 v35, v35
	v_exp_f32_e32 v51, v51
	v_exp_f32_e32 v36, v36
	v_exp_f32_e32 v52, v52
	v_exp_f32_e32 v37, v37
	v_exp_f32_e32 v53, v53
	v_exp_f32_e32 v38, v38
	v_exp_f32_e32 v54, v54
	v_exp_f32_e32 v39, v39
	v_exp_f32_e32 v55, v55
	v_exp_f32_e32 v40, v40
	v_exp_f32_e32 v56, v56
	v_exp_f32_e32 v41, v41
	v_exp_f32_e32 v57, v57
	v_exp_f32_e32 v42, v42
	v_exp_f32_e32 v58, v58
	v_exp_f32_e32 v43, v43
	v_exp_f32_e32 v59, v59
	v_exp_f32_e32 v44, v44
	v_exp_f32_e32 v60, v60
	v_exp_f32_e32 v45, v45
	v_exp_f32_e32 v61, v61
	v_exp_f32_e32 v46, v46
	v_exp_f32_e32 v62, v62
	v_exp_f32_e32 v47, v47
	v_exp_f32_e32 v63, v63
	s_waitcnt lgkmcnt(0)
	global_load_dwordx4 v[120:123], v129, s[4:5]
	global_load_dwordx4 v[124:127], v129, s[4:5] offset:128
	global_load_dwordx4 v[132:135], v130, s[6:7]
	s_add_u32 s4, s4, 0x40000
	s_addc_u32 s5, s5, 0
	s_add_u32 s6, s6, 0x1000
	s_addc_u32 s7, s7, 0
	v_add_f32_e32 v175, v32, v33
	v_add_f32_e32 v174, v48, v49
	v_add_f32_e32 v175, v175, v34
	v_add_f32_e32 v174, v174, v50
	v_add_f32_e32 v175, v175, v35
	v_add_f32_e32 v174, v174, v51
	v_add_f32_e32 v175, v175, v36
	v_add_f32_e32 v174, v174, v52
	v_add_f32_e32 v175, v175, v37
	v_add_f32_e32 v174, v174, v53
	v_add_f32_e32 v175, v175, v38
	v_add_f32_e32 v174, v174, v54
	v_add_f32_e32 v175, v175, v39
	v_add_f32_e32 v174, v174, v55
	v_add_f32_e32 v175, v175, v40
	v_add_f32_e32 v174, v174, v56
	v_add_f32_e32 v175, v175, v41
	v_add_f32_e32 v174, v174, v57
	v_add_f32_e32 v175, v175, v42
	v_add_f32_e32 v174, v174, v58
	v_add_f32_e32 v175, v175, v43
	v_add_f32_e32 v174, v174, v59
	v_add_f32_e32 v175, v175, v44
	v_add_f32_e32 v174, v174, v60
	v_add_f32_e32 v175, v175, v45
	v_add_f32_e32 v174, v174, v61
	v_add_f32_e32 v175, v175, v46
	v_add_f32_e32 v174, v174, v62
	v_add_f32_e32 v175, v175, v47
	v_add_f32_e32 v174, v174, v63
	v_add_f32_e32 v175, v175, v174
	v_cmp_ge_f32_e32 vcc, s23, v175
	s_cmp_eq_u64 vcc, exec
	s_cbranch_scc0 .Lat_rare3
; __device__ __forceinline__ void at_qkt(f32x16& p0, f32x16& p1, const char* Ks, const bf16x8* qr, int r32, int hi, float negm) {
; #pragma unroll
;   for (int r = 0; r < 16; ++r) { p0[r] = negm; p1[r] = negm; }
; #pragma unroll
;   for (int d0 = 0; d0 < 6; ++d0) {
;     const bf16x8 b0 = *(const bf16x8*)(Ks + r32 * AT_KROW + d0 * 32 + hi * 16);
;     const bf16x8 b1 = *(const bf16x8*)(Ks + (32 + r32) * AT_KROW + d0 * 32 + hi * 16);
;     p0 = MFMA(b0, qr[d0], p0);
;     p1 = MFMA(b1, qr[d0], p1);
;   }
; }
; __device__ __forceinline__ int v_st(int k, int c) { const int kk = (k & ~0xC) | ((k & 4) << 1) | ((k & 8) >> 1); return ((kk >> 3) * 4 + (c >> 5)) * 512 + ((kk & 7) * 32 + (c & 31)) * 2; }
; __device__ __forceinline__ int v_rd_base(int lane) { return ((lane & 3) << 3) | (((lane >> 2) & 3) << 6) | (((lane >> 4) & 1) << 5) | (((lane >> 5) & 1) << 8); }
; template <int OFF> __device__ __forceinline__ s16x4 tr_read(int vb) {
;   s16x4 r; asm volatile("ds_read_b64_tr_b16 %0, %1 offset:%2" : "=&v"(r) : "v"(vb), "i"(OFF) : "memory"); return r;
; }
; template <int D0> __device__ __forceinline__ void pv_one(f32x16& od, int vb, bf16x8 pa0, bf16x8 pa1, bf16x8 pa2, bf16x8 pa3) {
;   const s16x4 l0 = tr_read<v_rd_off(D0, 0, 0)>(vb), h0 = tr_read<v_rd_off(D0, 0, 1)>(vb), l1 = tr_read<v_rd_off(D0, 1, 0)>(vb), h1 = tr_read<v_rd_off(D0, 1, 1)>(vb);
;   const s16x4 l2 = tr_read<v_rd_off(D0, 2, 0)>(vb), h2 = tr_read<v_rd_off(D0, 2, 1)>(vb), l3 = tr_read<v_rd_off(D0, 3, 0)>(vb), h3 = tr_read<v_rd_off(D0, 3, 1)>(vb);
;   asm volatile("s_waitcnt lgkmcnt(0)" ::: "memory"); SBAR();
;     ...
;   od = MFMA(pa0, PK(l0, h0), od);
;   od = MFMA(pa1, PK(l1, h1), od);
;   od = MFMA(pa2, PK(l2, h2), od);
;   od = MFMA(pa3, PK(l3, h3), od);
;     ...
; }
; __device__ __forceinline__ void pv_d0(f32x16* o, int vb, bf16x8 pa0, bf16x8 pa1, bf16x8 pa2, bf16x8 pa3) {
;   pv_one<0>(o[0], vb, pa0, pa1, pa2, pa3); pv_one<1>(o[1], vb, pa0, pa1, pa2, pa3);
; __device__ void phase_attn(const Params& p, char* lds) {
;     ...
;     for (int j = 1; j + 1 < NT; j += 2) {
;       SBAR(); at_qkt(pB0, pB1, K_lds + AT_SHMK, qr, r32, hi, -m_reg);
;       at_finishSM(pA0, pA1, alA, l_reg, pa0, pa1, pa2, pa3); SBAR();
;       SLOAD(1, (j + 2) * 64); SBAR();
;       pv_d0(o, vb0, pa0, pa1, pa2, pa3); at_partialSM(pB0, pB1, m_reg, alB, false);
;       __syncthreads(); SWAIT(); SWRITE(0, 0);
;       RESC(alB); __syncthreads();
.Lat_rare3_back:
	v_add_f32_e32 v173, v173, v175
	v_cvt_pk_bf16_f32 v104, v32, v33
	v_cvt_pk_bf16_f32 v105, v34, v35
	v_cvt_pk_bf16_f32 v106, v36, v37
	v_cvt_pk_bf16_f32 v107, v38, v39
	v_cvt_pk_bf16_f32 v108, v40, v41
	v_cvt_pk_bf16_f32 v109, v42, v43
	v_cvt_pk_bf16_f32 v110, v44, v45
	v_cvt_pk_bf16_f32 v111, v46, v47
	v_cvt_pk_bf16_f32 v112, v48, v49
	v_cvt_pk_bf16_f32 v113, v50, v51
	v_cvt_pk_bf16_f32 v114, v52, v53
	v_cvt_pk_bf16_f32 v115, v54, v55
	v_cvt_pk_bf16_f32 v116, v56, v57
	v_cvt_pk_bf16_f32 v117, v58, v59
	v_cvt_pk_bf16_f32 v118, v60, v61
	v_cvt_pk_bf16_f32 v119, v62, v63
	ds_read_b128 v[184:187], v170 offset:13312
	ds_read_b128 v[188:191], v170 offset:19968
	ds_read_b128 v[192:195], v170 offset:13344
	ds_read_b128 v[196:199], v170 offset:20000
	ds_read_b128 v[200:203], v170 offset:13376
	ds_read_b128 v[204:207], v170 offset:20032
	ds_read_b128 v[208:211], v170 offset:13408
	ds_read_b128 v[212:215], v170 offset:20064
	s_barrier
	s_sub_u32 s13, s13, 1
	s_cmp_lg_u32 s13, 0
	s_cbranch_scc1 .Lat_loop
	s_waitcnt lgkmcnt(6)
	v_mfma_f32_32x32x16_bf16 v[32:47], v[184:187], v[80:83], v[64:79]
	v_mfma_f32_32x32x16_bf16 v[48:63], v[188:191], v[80:83], v[64:79]
	ds_read_b128 v[184:187], v170 offset:13440
	ds_read_b128 v[188:191], v170 offset:20096
	s_waitcnt lgkmcnt(6)
	v_mfma_f32_32x32x16_bf16 v[32:47], v[192:195], v[84:87], v[32:47]
	v_mfma_f32_32x32x16_bf16 v[48:63], v[196:199], v[84:87], v[48:63]
	ds_read_b128 v[192:195], v170 offset:13472
	ds_read_b128 v[196:199], v170 offset:20128
	s_waitcnt lgkmcnt(6)
	v_mfma_f32_32x32x16_bf16 v[32:47], v[200:203], v[88:91], v[32:47]
	v_mfma_f32_32x32x16_bf16 v[48:63], v[204:207], v[88:91], v[48:63]
	s_waitcnt lgkmcnt(4)
	v_mfma_f32_32x32x16_bf16 v[32:47], v[208:211], v[92:95], v[32:47]
	v_mfma_f32_32x32x16_bf16 v[48:63], v[212:215], v[92:95], v[48:63]
	ds_read_b64_tr_b16 v[148:149], v171 offset:0
	ds_read_b64_tr_b16 v[150:151], v171 offset:2048
	ds_read_b64_tr_b16 v[152:153], v171 offset:4096
	ds_read_b64_tr_b16 v[154:155], v171 offset:6144
	s_waitcnt lgkmcnt(6)
	v_mfma_f32_32x32x16_bf16 v[32:47], v[184:187], v[96:99], v[32:47]
	v_mfma_f32_32x32x16_bf16 v[48:63], v[188:191], v[96:99], v[48:63]
	ds_read_b64_tr_b16 v[156:157], v171 offset:8192
	ds_read_b64_tr_b16 v[158:159], v171 offset:10240
	ds_read_b64_tr_b16 v[216:217], v171 offset:12288
	ds_read_b64_tr_b16 v[218:219], v171 offset:14336
	s_waitcnt lgkmcnt(8)
	v_mfma_f32_32x32x16_bf16 v[32:47], v[192:195], v[100:103], v[32:47]
	v_mfma_f32_32x32x16_bf16 v[48:63], v[196:199], v[100:103], v[48:63]
	ds_read_b64_tr_b16 v[220:221], v171 offset:512
	ds_read_b64_tr_b16 v[222:223], v171 offset:2560
	ds_read_b64_tr_b16 v[224:225], v171 offset:4608
	ds_read_b64_tr_b16 v[226:227], v171 offset:6656
	s_waitcnt lgkmcnt(10)
	v_mfma_f32_32x32x16_bf16 v[0:15], v[104:107], v[148:151], v[0:15]
	s_waitcnt lgkmcnt(8)
	v_mfma_f32_32x32x16_bf16 v[0:15], v[108:111], v[152:155], v[0:15]
	ds_read_b64_tr_b16 v[236:237], v171 offset:8704
	ds_read_b64_tr_b16 v[238:239], v171 offset:10752
	ds_read_b64_tr_b16 v[240:241], v171 offset:12800
	ds_read_b64_tr_b16 v[242:243], v171 offset:14848
	s_waitcnt lgkmcnt(10)
	v_mfma_f32_32x32x16_bf16 v[0:15], v[112:115], v[156:159], v[0:15]
	s_waitcnt lgkmcnt(8)
	v_mfma_f32_32x32x16_bf16 v[0:15], v[116:119], v[216:219], v[0:15]
	s_waitcnt lgkmcnt(6)
	v_mfma_f32_32x32x16_bf16 v[16:31], v[104:107], v[220:223], v[16:31]
	s_waitcnt lgkmcnt(4)
	v_mfma_f32_32x32x16_bf16 v[16:31], v[108:111], v[224:227], v[16:31]
	s_waitcnt lgkmcnt(2)
	v_mfma_f32_32x32x16_bf16 v[16:31], v[112:115], v[236:239], v[16:31]
	s_waitcnt lgkmcnt(0)
	v_mfma_f32_32x32x16_bf16 v[16:31], v[116:119], v[240:243], v[16:31]
	s_barrier
	s_waitcnt vmcnt(0)
	ds_write_b128 v167, v[120:123] offset:39936
	ds_write_b128 v131, v[124:127] offset:49152
	ds_write_b128 v169, v[132:135] offset:39936
	v_exp_f32_e32 v32, v32
	v_exp_f32_e32 v48, v48
	v_exp_f32_e32 v33, v33
	v_exp_f32_e32 v49, v49
	v_exp_f32_e32 v34, v34
	v_exp_f32_e32 v50, v50
	v_exp_f32_e32 v35, v35
	v_exp_f32_e32 v51, v51
	v_exp_f32_e32 v36, v36
	v_exp_f32_e32 v52, v52
	v_exp_f32_e32 v37, v37
	v_exp_f32_e32 v53, v53
	v_exp_f32_e32 v38, v38
	v_exp_f32_e32 v54, v54
	v_exp_f32_e32 v39, v39
	v_exp_f32_e32 v55, v55
	v_exp_f32_e32 v40, v40
	v_exp_f32_e32 v56, v56
	v_exp_f32_e32 v41, v41
	v_exp_f32_e32 v57, v57
	v_exp_f32_e32 v42, v42
	v_exp_f32_e32 v58, v58
	v_exp_f32_e32 v43, v43
	v_exp_f32_e32 v59, v59
	v_exp_f32_e32 v44, v44
	v_exp_f32_e32 v60, v60
	v_exp_f32_e32 v45, v45
	v_exp_f32_e32 v61, v61
	v_exp_f32_e32 v46, v46
	v_exp_f32_e32 v62, v62
	v_exp_f32_e32 v47, v47
	v_exp_f32_e32 v63, v63
	s_waitcnt lgkmcnt(0)
	v_add_f32_e32 v175, v32, v33
	v_add_f32_e32 v174, v48, v49
	v_add_f32_e32 v175, v175, v34
	v_add_f32_e32 v174, v174, v50
	v_add_f32_e32 v175, v175, v35
	v_add_f32_e32 v174, v174, v51
	v_add_f32_e32 v175, v175, v36
	v_add_f32_e32 v174, v174, v52
	v_add_f32_e32 v175, v175, v37
	v_add_f32_e32 v174, v174, v53
	v_add_f32_e32 v175, v175, v38
	v_add_f32_e32 v174, v174, v54
	v_add_f32_e32 v175, v175, v39
	v_add_f32_e32 v174, v174, v55
	v_add_f32_e32 v175, v175, v40
	v_add_f32_e32 v174, v174, v56
	v_add_f32_e32 v175, v175, v41
	v_add_f32_e32 v174, v174, v57
	v_add_f32_e32 v175, v175, v42
	v_add_f32_e32 v174, v174, v58
	v_add_f32_e32 v175, v175, v43
	v_add_f32_e32 v174, v174, v59
	v_add_f32_e32 v175, v175, v44
	v_add_f32_e32 v174, v174, v60
	v_add_f32_e32 v175, v175, v45
	v_add_f32_e32 v174, v174, v61
	v_add_f32_e32 v175, v175, v46
	v_add_f32_e32 v174, v174, v62
	v_add_f32_e32 v175, v175, v47
	v_add_f32_e32 v174, v174, v63
	v_add_f32_e32 v175, v175, v174
	v_cmp_ge_f32_e32 vcc, s23, v175
	s_cmp_eq_u64 vcc, exec
	s_cbranch_scc0 .Lat_rare_t129
; #define SBAR() __builtin_amdgcn_sched_barrier(0)
; __device__ __forceinline__ void at_qkt(f32x16& p0, f32x16& p1, const char* Ks, const bf16x8* qr, int r32, int hi, float negm) {
; #pragma unroll
;   for (int r = 0; r < 16; ++r) { p0[r] = negm; p1[r] = negm; }
; #pragma unroll
;   for (int d0 = 0; d0 < 6; ++d0) {
;     const bf16x8 b0 = *(const bf16x8*)(Ks + r32 * AT_KROW + d0 * 32 + hi * 16);
;     const bf16x8 b1 = *(const bf16x8*)(Ks + (32 + r32) * AT_KROW + d0 * 32 + hi * 16);
;     p0 = MFMA(b0, qr[d0], p0);
;     p1 = MFMA(b1, qr[d0], p1);
;   }
; }
; __device__ __forceinline__ int v_st(int k, int c) { const int kk = (k & ~0xC) | ((k & 4) << 1) | ((k & 8) >> 1); return ((kk >> 3) * 4 + (c >> 5)) * 512 + ((kk & 7) * 32 + (c & 31)) * 2; }
; __device__ __forceinline__ int v_rd_base(int lane) { return ((lane & 3) << 3) | (((lane >> 2) & 3) << 6) | (((lane >> 4) & 1) << 5) | (((lane >> 5) & 1) << 8); }
; template <int OFF> __device__ __forceinline__ s16x4 tr_read(int vb) {
;   s16x4 r; asm volatile("ds_read_b64_tr_b16 %0, %1 offset:%2" : "=&v"(r) : "v"(vb), "i"(OFF) : "memory"); return r;
; }
; template <int D0> __device__ __forceinline__ void pv_one(f32x16& od, int vb, bf16x8 pa0, bf16x8 pa1, bf16x8 pa2, bf16x8 pa3) {
;   const s16x4 l0 = tr_read<v_rd_off(D0, 0, 0)>(vb), h0 = tr_read<v_rd_off(D0, 0, 1)>(vb), l1 = tr_read<v_rd_off(D0, 1, 0)>(vb), h1 = tr_read<v_rd_off(D0, 1, 1)>(vb);
;   const s16x4 l2 = tr_read<v_rd_off(D0, 2, 0)>(vb), h2 = tr_read<v_rd_off(D0, 2, 1)>(vb), l3 = tr_read<v_rd_off(D0, 3, 0)>(vb), h3 = tr_read<v_rd_off(D0, 3, 1)>(vb);
;   asm volatile("s_waitcnt lgkmcnt(0)" ::: "memory"); SBAR();
;     ...
;   od = MFMA(pa0, PK(l0, h0), od);
;   od = MFMA(pa1, PK(l1, h1), od);
;   od = MFMA(pa2, PK(l2, h2), od);
;   od = MFMA(pa3, PK(l3, h3), od);
;     ...
; }
; __device__ __forceinline__ void pv_d0(f32x16* o, int vb, bf16x8 pa0, bf16x8 pa1, bf16x8 pa2, bf16x8 pa3) {
;   pv_one<0>(o[0], vb, pa0, pa1, pa2, pa3); pv_one<1>(o[1], vb, pa0, pa1, pa2, pa3);
; __device__ void phase_attn(const Params& p, char* lds) {
;     ...
;     SBAR(); at_qkt(pB0, pB1, K_lds + AT_SHMK, qr, r32, hi, -m_reg);
;     at_finishSM(pA0, pA1, alA, l_reg, pa0, pa1, pa2, pa3); SBAR();
;     pv_d0(o, vb0, pa0, pa1, pa2, pa3); at_partialSM(pB0, pB1, m_reg, alB, false);
;     __syncthreads(); RESC(alB);
;     at_finishSM(pB0, pB1, alB, l_reg, pa0, pa1, pa2, pa3); SBAR();
.Lat_rare_t129_back:
	v_add_f32_e32 v173, v173, v175
	v_cvt_pk_bf16_f32 v104, v32, v33
	v_cvt_pk_bf16_f32 v105, v34, v35
	v_cvt_pk_bf16_f32 v106, v36, v37
	v_cvt_pk_bf16_f32 v107, v38, v39
	v_cvt_pk_bf16_f32 v108, v40, v41
	v_cvt_pk_bf16_f32 v109, v42, v43
	v_cvt_pk_bf16_f32 v110, v44, v45
	v_cvt_pk_bf16_f32 v111, v46, v47
	v_cvt_pk_bf16_f32 v112, v48, v49
	v_cvt_pk_bf16_f32 v113, v50, v51
	v_cvt_pk_bf16_f32 v114, v52, v53
	v_cvt_pk_bf16_f32 v115, v54, v55
	v_cvt_pk_bf16_f32 v116, v56, v57
	v_cvt_pk_bf16_f32 v117, v58, v59
	v_cvt_pk_bf16_f32 v118, v60, v61
	v_cvt_pk_bf16_f32 v119, v62, v63
	ds_read_b128 v[184:187], v170 offset:26624
	ds_read_b128 v[188:191], v170 offset:33280
	ds_read_b128 v[192:195], v170 offset:26656
	ds_read_b128 v[196:199], v170 offset:33312
	ds_read_b128 v[200:203], v170 offset:26688
	ds_read_b128 v[204:207], v170 offset:33344
	ds_read_b128 v[208:211], v170 offset:26720
	ds_read_b128 v[212:215], v170 offset:33376
	s_barrier
	s_waitcnt lgkmcnt(6)
	v_mfma_f32_32x32x16_bf16 v[32:47], v[184:187], v[80:83], v[64:79]
	v_mfma_f32_32x32x16_bf16 v[48:63], v[188:191], v[80:83], v[64:79]
	ds_read_b128 v[184:187], v170 offset:26752
	ds_read_b128 v[188:191], v170 offset:33408
	s_waitcnt lgkmcnt(6)
	v_mfma_f32_32x32x16_bf16 v[32:47], v[192:195], v[84:87], v[32:47]
	v_mfma_f32_32x32x16_bf16 v[48:63], v[196:199], v[84:87], v[48:63]
	ds_read_b128 v[192:195], v170 offset:26784
	ds_read_b128 v[196:199], v170 offset:33440
	s_waitcnt lgkmcnt(6)
	v_mfma_f32_32x32x16_bf16 v[32:47], v[200:203], v[88:91], v[32:47]
	v_mfma_f32_32x32x16_bf16 v[48:63], v[204:207], v[88:91], v[48:63]
	s_waitcnt lgkmcnt(4)
	v_mfma_f32_32x32x16_bf16 v[32:47], v[208:211], v[92:95], v[32:47]
	v_mfma_f32_32x32x16_bf16 v[48:63], v[212:215], v[92:95], v[48:63]
	ds_read_b64_tr_b16 v[148:149], v171 offset:16384
	ds_read_b64_tr_b16 v[150:151], v171 offset:18432
	ds_read_b64_tr_b16 v[152:153], v171 offset:20480
	ds_read_b64_tr_b16 v[154:155], v171 offset:22528
	s_waitcnt lgkmcnt(6)
	v_mfma_f32_32x32x16_bf16 v[32:47], v[184:187], v[96:99], v[32:47]
	v_mfma_f32_32x32x16_bf16 v[48:63], v[188:191], v[96:99], v[48:63]
	ds_read_b64_tr_b16 v[156:157], v171 offset:24576
	ds_read_b64_tr_b16 v[158:159], v171 offset:26624
	ds_read_b64_tr_b16 v[216:217], v171 offset:28672
	ds_read_b64_tr_b16 v[218:219], v171 offset:30720
	s_waitcnt lgkmcnt(8)
	v_mfma_f32_32x32x16_bf16 v[32:47], v[192:195], v[100:103], v[32:47]
	v_mfma_f32_32x32x16_bf16 v[48:63], v[196:199], v[100:103], v[48:63]
	ds_read_b64_tr_b16 v[220:221], v171 offset:16896
	ds_read_b64_tr_b16 v[222:223], v171 offset:18944
	ds_read_b64_tr_b16 v[224:225], v171 offset:20992
	ds_read_b64_tr_b16 v[226:227], v171 offset:23040
	s_waitcnt lgkmcnt(10)
	v_mfma_f32_32x32x16_bf16 v[0:15], v[104:107], v[148:151], v[0:15]
	s_waitcnt lgkmcnt(8)
	v_mfma_f32_32x32x16_bf16 v[0:15], v[108:111], v[152:155], v[0:15]
	ds_read_b64_tr_b16 v[236:237], v171 offset:25088
	ds_read_b64_tr_b16 v[238:239], v171 offset:27136
	ds_read_b64_tr_b16 v[240:241], v171 offset:29184
	ds_read_b64_tr_b16 v[242:243], v171 offset:31232
	s_waitcnt lgkmcnt(10)
	v_mfma_f32_32x32x16_bf16 v[0:15], v[112:115], v[156:159], v[0:15]
	s_waitcnt lgkmcnt(8)
	v_mfma_f32_32x32x16_bf16 v[0:15], v[116:119], v[216:219], v[0:15]
	s_waitcnt lgkmcnt(6)
	v_mfma_f32_32x32x16_bf16 v[16:31], v[104:107], v[220:223], v[16:31]
	s_waitcnt lgkmcnt(4)
	v_mfma_f32_32x32x16_bf16 v[16:31], v[108:111], v[224:227], v[16:31]
	s_waitcnt lgkmcnt(2)
	v_mfma_f32_32x32x16_bf16 v[16:31], v[112:115], v[236:239], v[16:31]
	s_waitcnt lgkmcnt(0)
	v_mfma_f32_32x32x16_bf16 v[16:31], v[116:119], v[240:243], v[16:31]
	s_barrier
	v_exp_f32_e32 v32, v32
	v_exp_f32_e32 v48, v48
	v_exp_f32_e32 v33, v33
	v_exp_f32_e32 v49, v49
	v_exp_f32_e32 v34, v34
	v_exp_f32_e32 v50, v50
	v_exp_f32_e32 v35, v35
	v_exp_f32_e32 v51, v51
	v_exp_f32_e32 v36, v36
	v_exp_f32_e32 v52, v52
	v_exp_f32_e32 v37, v37
	v_exp_f32_e32 v53, v53
	v_exp_f32_e32 v38, v38
	v_exp_f32_e32 v54, v54
	v_exp_f32_e32 v39, v39
	v_exp_f32_e32 v55, v55
	v_exp_f32_e32 v40, v40
	v_exp_f32_e32 v56, v56
	v_exp_f32_e32 v41, v41
	v_exp_f32_e32 v57, v57
	v_exp_f32_e32 v42, v42
	v_exp_f32_e32 v58, v58
	v_exp_f32_e32 v43, v43
	v_exp_f32_e32 v59, v59
	v_exp_f32_e32 v44, v44
	v_exp_f32_e32 v60, v60
	v_exp_f32_e32 v45, v45
	v_exp_f32_e32 v61, v61
	v_exp_f32_e32 v46, v46
	v_exp_f32_e32 v62, v62
	v_exp_f32_e32 v47, v47
	v_exp_f32_e32 v63, v63
	v_add_f32_e32 v175, v32, v33
	v_add_f32_e32 v174, v48, v49
	v_add_f32_e32 v175, v175, v34
	v_add_f32_e32 v174, v174, v50
	v_add_f32_e32 v175, v175, v35
	v_add_f32_e32 v174, v174, v51
	v_add_f32_e32 v175, v175, v36
	v_add_f32_e32 v174, v174, v52
	v_add_f32_e32 v175, v175, v37
	v_add_f32_e32 v174, v174, v53
	v_add_f32_e32 v175, v175, v38
	v_add_f32_e32 v174, v174, v54
	v_add_f32_e32 v175, v175, v39
	v_add_f32_e32 v174, v174, v55
	v_add_f32_e32 v175, v175, v40
	v_add_f32_e32 v174, v174, v56
	v_add_f32_e32 v175, v175, v41
	v_add_f32_e32 v174, v174, v57
	v_add_f32_e32 v175, v175, v42
	v_add_f32_e32 v174, v174, v58
	v_add_f32_e32 v175, v175, v43
	v_add_f32_e32 v174, v174, v59
	v_add_f32_e32 v175, v175, v44
	v_add_f32_e32 v174, v174, v60
	v_add_f32_e32 v175, v175, v45
	v_add_f32_e32 v174, v174, v61
	v_add_f32_e32 v175, v175, v46
	v_add_f32_e32 v174, v174, v62
	v_add_f32_e32 v175, v175, v47
	v_add_f32_e32 v174, v174, v63
	v_add_f32_e32 v175, v175, v174
	v_cmp_ge_f32_e32 vcc, s23, v175
	s_cmp_eq_u64 vcc, exec
	s_cbranch_scc0 .Lat_rare_t130
; __device__ __forceinline__ void at_qkt(f32x16& p0, f32x16& p1, const char* Ks, const bf16x8* qr, int r32, int hi, float negm) {
; #pragma unroll
;   for (int r = 0; r < 16; ++r) { p0[r] = negm; p1[r] = negm; }
; #pragma unroll
;   for (int d0 = 0; d0 < 6; ++d0) {
;     const bf16x8 b0 = *(const bf16x8*)(Ks + r32 * AT_KROW + d0 * 32 + hi * 16);
;     const bf16x8 b1 = *(const bf16x8*)(Ks + (32 + r32) * AT_KROW + d0 * 32 + hi * 16);
;     p0 = MFMA(b0, qr[d0], p0);
;     p1 = MFMA(b1, qr[d0], p1);
;   }
; }
; __device__ __forceinline__ int v_st(int k, int c) { const int kk = (k & ~0xC) | ((k & 4) << 1) | ((k & 8) >> 1); return ((kk >> 3) * 4 + (c >> 5)) * 512 + ((kk & 7) * 32 + (c & 31)) * 2; }
; __device__ __forceinline__ int v_rd_base(int lane) { return ((lane & 3) << 3) | (((lane >> 2) & 3) << 6) | (((lane >> 4) & 1) << 5) | (((lane >> 5) & 1) << 8); }
; template <int OFF> __device__ __forceinline__ s16x4 tr_read(int vb) {
;   s16x4 r; asm volatile("ds_read_b64_tr_b16 %0, %1 offset:%2" : "=&v"(r) : "v"(vb), "i"(OFF) : "memory"); return r;
; }
; template <int D0> __device__ __forceinline__ void pv_one(f32x16& od, int vb, bf16x8 pa0, bf16x8 pa1, bf16x8 pa2, bf16x8 pa3) {
;   const s16x4 l0 = tr_read<v_rd_off(D0, 0, 0)>(vb), h0 = tr_read<v_rd_off(D0, 0, 1)>(vb), l1 = tr_read<v_rd_off(D0, 1, 0)>(vb), h1 = tr_read<v_rd_off(D0, 1, 1)>(vb);
;   const s16x4 l2 = tr_read<v_rd_off(D0, 2, 0)>(vb), h2 = tr_read<v_rd_off(D0, 2, 1)>(vb), l3 = tr_read<v_rd_off(D0, 3, 0)>(vb), h3 = tr_read<v_rd_off(D0, 3, 1)>(vb);
;   asm volatile("s_waitcnt lgkmcnt(0)" ::: "memory"); SBAR();
;     ...
;   od = MFMA(pa0, PK(l0, h0), od);
;   od = MFMA(pa1, PK(l1, h1), od);
;   od = MFMA(pa2, PK(l2, h2), od);
;   od = MFMA(pa3, PK(l3, h3), od);
;     ...
; }
; __device__ __forceinline__ void pv_d0(f32x16* o, int vb, bf16x8 pa0, bf16x8 pa1, bf16x8 pa2, bf16x8 pa3) {
;   pv_one<0>(o[0], vb, pa0, pa1, pa2, pa3); pv_one<1>(o[1], vb, pa0, pa1, pa2, pa3);
; __device__ void phase_attn(const Params& p, char* lds) {
;     ...
;     SBAR(); at_qkt(pB0, pB1, K_lds + AT_SHMK, qr, r32, hi, -m_reg);
;     at_finishSM(pA0, pA1, alA, l_reg, pa0, pa1, pa2, pa3); SBAR();
;     pv_d0(o, vb0, pa0, pa1, pa2, pa3); at_partialSM(pB0, pB1, m_reg, alB, false);
;     __syncthreads(); RESC(alB);
;     at_finishSM(pB0, pB1, alB, l_reg, pa0, pa1, pa2, pa3); SBAR();
;     pv_d0(o, vb0 + AT_SHMV, pa0, pa1, pa2, pa3);
.Lat_rare_t130_back:
	v_add_f32_e32 v173, v173, v175
	v_cvt_pk_bf16_f32 v104, v32, v33
	v_cvt_pk_bf16_f32 v105, v34, v35
	v_cvt_pk_bf16_f32 v106, v36, v37
	v_cvt_pk_bf16_f32 v107, v38, v39
	v_cvt_pk_bf16_f32 v108, v40, v41
	v_cvt_pk_bf16_f32 v109, v42, v43
	v_cvt_pk_bf16_f32 v110, v44, v45
	v_cvt_pk_bf16_f32 v111, v46, v47
	v_cvt_pk_bf16_f32 v112, v48, v49
	v_cvt_pk_bf16_f32 v113, v50, v51
	v_cvt_pk_bf16_f32 v114, v52, v53
	v_cvt_pk_bf16_f32 v115, v54, v55
	v_cvt_pk_bf16_f32 v116, v56, v57
	v_cvt_pk_bf16_f32 v117, v58, v59
	v_cvt_pk_bf16_f32 v118, v60, v61
	v_cvt_pk_bf16_f32 v119, v62, v63
	ds_read_b128 v[184:187], v170 offset:39936
	ds_read_b128 v[188:191], v170 offset:46592
	ds_read_b128 v[192:195], v170 offset:39968
	ds_read_b128 v[196:199], v170 offset:46624
	ds_read_b128 v[200:203], v170 offset:40000
	ds_read_b128 v[204:207], v170 offset:46656
	ds_read_b128 v[208:211], v170 offset:40032
	ds_read_b128 v[212:215], v170 offset:46688
	s_barrier
	s_waitcnt lgkmcnt(6)
	v_mfma_f32_32x32x16_bf16 v[32:47], v[184:187], v[80:83], v[64:79]
	v_mfma_f32_32x32x16_bf16 v[48:63], v[188:191], v[80:83], v[64:79]
	ds_read_b128 v[184:187], v170 offset:40064
	ds_read_b128 v[188:191], v170 offset:46720
	s_waitcnt lgkmcnt(6)
	v_mfma_f32_32x32x16_bf16 v[32:47], v[192:195], v[84:87], v[32:47]
	v_mfma_f32_32x32x16_bf16 v[48:63], v[196:199], v[84:87], v[48:63]
	ds_read_b128 v[192:195], v170 offset:40096
	ds_read_b128 v[196:199], v170 offset:46752
	s_waitcnt lgkmcnt(6)
	v_mfma_f32_32x32x16_bf16 v[32:47], v[200:203], v[88:91], v[32:47]
	v_mfma_f32_32x32x16_bf16 v[48:63], v[204:207], v[88:91], v[48:63]
	s_waitcnt lgkmcnt(4)
	v_mfma_f32_32x32x16_bf16 v[32:47], v[208:211], v[92:95], v[32:47]
	v_mfma_f32_32x32x16_bf16 v[48:63], v[212:215], v[92:95], v[48:63]
	ds_read_b64_tr_b16 v[148:149], v171 offset:32768
	ds_read_b64_tr_b16 v[150:151], v171 offset:34816
	ds_read_b64_tr_b16 v[152:153], v171 offset:36864
	ds_read_b64_tr_b16 v[154:155], v171 offset:38912
	s_waitcnt lgkmcnt(6)
	v_mfma_f32_32x32x16_bf16 v[32:47], v[184:187], v[96:99], v[32:47]
	v_mfma_f32_32x32x16_bf16 v[48:63], v[188:191], v[96:99], v[48:63]
	ds_read_b64_tr_b16 v[156:157], v171 offset:40960
	ds_read_b64_tr_b16 v[158:159], v171 offset:43008
	ds_read_b64_tr_b16 v[216:217], v171 offset:45056
	ds_read_b64_tr_b16 v[218:219], v171 offset:47104
	s_waitcnt lgkmcnt(8)
	v_mfma_f32_32x32x16_bf16 v[32:47], v[192:195], v[100:103], v[32:47]
	v_mfma_f32_32x32x16_bf16 v[48:63], v[196:199], v[100:103], v[48:63]
	ds_read_b64_tr_b16 v[220:221], v171 offset:33280
	ds_read_b64_tr_b16 v[222:223], v171 offset:35328
	ds_read_b64_tr_b16 v[224:225], v171 offset:37376
	ds_read_b64_tr_b16 v[226:227], v171 offset:39424
	s_waitcnt lgkmcnt(10)
	v_mfma_f32_32x32x16_bf16 v[0:15], v[104:107], v[148:151], v[0:15]
	s_waitcnt lgkmcnt(8)
	v_mfma_f32_32x32x16_bf16 v[0:15], v[108:111], v[152:155], v[0:15]
	ds_read_b64_tr_b16 v[236:237], v171 offset:41472
	ds_read_b64_tr_b16 v[238:239], v171 offset:43520
	ds_read_b64_tr_b16 v[240:241], v171 offset:45568
	ds_read_b64_tr_b16 v[242:243], v171 offset:47616
	s_waitcnt lgkmcnt(10)
	v_mfma_f32_32x32x16_bf16 v[0:15], v[112:115], v[156:159], v[0:15]
	s_waitcnt lgkmcnt(8)
	v_mfma_f32_32x32x16_bf16 v[0:15], v[116:119], v[216:219], v[0:15]
	s_waitcnt lgkmcnt(6)
	v_mfma_f32_32x32x16_bf16 v[16:31], v[104:107], v[220:223], v[16:31]
	s_waitcnt lgkmcnt(4)
	v_mfma_f32_32x32x16_bf16 v[16:31], v[108:111], v[224:227], v[16:31]
	s_waitcnt lgkmcnt(2)
	v_mfma_f32_32x32x16_bf16 v[16:31], v[112:115], v[236:239], v[16:31]
	s_waitcnt lgkmcnt(0)
	v_mfma_f32_32x32x16_bf16 v[16:31], v[116:119], v[240:243], v[16:31]
	s_barrier
; __device__ __forceinline__ int crow(int r, int hi) { return (r & 3) + 8 * (r >> 2) + 4 * hi; }
; __device__ __forceinline__ void at_finishSM(f32x16& p0, f32x16& p1, float alpha, float& l_reg, bf16x8& pa0, bf16x8& pa1, bf16x8& pa2, bf16x8& pa3) {
; #pragma unroll
;   for (int r = 0; r < 16; ++r) p1[r] = __builtin_amdgcn_exp2f(p1[r]);
;   float ps = 0;
; #pragma unroll
;   for (int r = 0; r < 16; ++r) ps += p0[r];
; #pragma unroll
;   for (int r = 0; r < 16; ++r) ps += p1[r];
;   { auto rr = __builtin_amdgcn_permlane32_swap(__float_as_uint(ps), __float_as_uint(ps), false, false);
;     ps = __uint_as_float(rr[0]) + __uint_as_float(rr[1]); }
;   l_reg = l_reg * alpha + ps;
; __device__ void phase_attn(const Params& p, char* lds) {
;     ...
;     bf16_t* Gw = G1 + (row0 + qblk * 256 + wid * 32) * 1024 + h * 64 + r32;
;     bf16_t gin[32];
; #pragma unroll
;     for (int r = 0; r < 16; ++r) { gin[2 * r] = Gw[(size_t)crow(r, hi) * 1024]; gin[2 * r + 1] = Gw[(size_t)crow(r, hi) * 1024 + 32]; }
	s_add_u32 s8, s28, 0x0
	s_addc_u32 s9, s29, 0
	global_load_ushort v120, v235, s[8:9] offset:0
	global_load_ushort v121, v235, s[8:9] offset:64
	global_load_ushort v122, v235, s[8:9] offset:2048
	global_load_ushort v123, v235, s[8:9] offset:2112
	s_add_u32 s8, s28, 0x1000
	s_addc_u32 s9, s29, 0
	global_load_ushort v124, v235, s[8:9] offset:0
	global_load_ushort v125, v235, s[8:9] offset:64
	global_load_ushort v126, v235, s[8:9] offset:2048
	global_load_ushort v127, v235, s[8:9] offset:2112
	s_add_u32 s8, s28, 0x4000
	s_addc_u32 s9, s29, 0
	global_load_ushort v132, v235, s[8:9] offset:0
	global_load_ushort v133, v235, s[8:9] offset:64
	global_load_ushort v134, v235, s[8:9] offset:2048
	global_load_ushort v135, v235, s[8:9] offset:2112
	s_add_u32 s8, s28, 0x5000
	s_addc_u32 s9, s29, 0
	global_load_ushort v136, v235, s[8:9] offset:0
	global_load_ushort v137, v235, s[8:9] offset:64
	global_load_ushort v138, v235, s[8:9] offset:2048
	global_load_ushort v139, v235, s[8:9] offset:2112
	s_add_u32 s8, s28, 0x8000
	s_addc_u32 s9, s29, 0
	global_load_ushort v140, v235, s[8:9] offset:0
	global_load_ushort v141, v235, s[8:9] offset:64
	global_load_ushort v142, v235, s[8:9] offset:2048
	global_load_ushort v143, v235, s[8:9] offset:2112
	s_add_u32 s8, s28, 0x9000
	s_addc_u32 s9, s29, 0
	global_load_ushort v144, v235, s[8:9] offset:0
	global_load_ushort v145, v235, s[8:9] offset:64
	global_load_ushort v146, v235, s[8:9] offset:2048
	global_load_ushort v147, v235, s[8:9] offset:2112
	s_add_u32 s8, s28, 0xc000
	s_addc_u32 s9, s29, 0
	global_load_ushort v200, v235, s[8:9] offset:0
	global_load_ushort v201, v235, s[8:9] offset:64
	global_load_ushort v202, v235, s[8:9] offset:2048
	global_load_ushort v203, v235, s[8:9] offset:2112
	s_add_u32 s8, s28, 0xd000
	s_addc_u32 s9, s29, 0
	global_load_ushort v204, v235, s[8:9] offset:0
	global_load_ushort v205, v235, s[8:9] offset:64
	global_load_ushort v206, v235, s[8:9] offset:2048
	global_load_ushort v207, v235, s[8:9] offset:2112
	v_exp_f32_e32 v32, v32
	v_exp_f32_e32 v48, v48
	v_exp_f32_e32 v33, v33
	v_exp_f32_e32 v49, v49
	v_exp_f32_e32 v34, v34
	v_exp_f32_e32 v50, v50
	v_exp_f32_e32 v35, v35
	v_exp_f32_e32 v51, v51
	v_exp_f32_e32 v36, v36
	v_exp_f32_e32 v52, v52
	v_exp_f32_e32 v37, v37
	v_exp_f32_e32 v53, v53
	v_exp_f32_e32 v38, v38
	v_exp_f32_e32 v54, v54
	v_exp_f32_e32 v39, v39
	v_exp_f32_e32 v55, v55
	v_exp_f32_e32 v40, v40
	v_exp_f32_e32 v56, v56
	v_exp_f32_e32 v41, v41
	v_exp_f32_e32 v57, v57
	v_exp_f32_e32 v42, v42
	v_exp_f32_e32 v58, v58
	v_exp_f32_e32 v43, v43
	v_exp_f32_e32 v59, v59
	v_exp_f32_e32 v44, v44
	v_exp_f32_e32 v60, v60
	v_exp_f32_e32 v45, v45
	v_exp_f32_e32 v61, v61
	v_exp_f32_e32 v46, v46
	v_exp_f32_e32 v62, v62
	v_exp_f32_e32 v47, v47
	v_exp_f32_e32 v63, v63
	v_add_f32_e32 v175, v32, v33
	v_add_f32_e32 v174, v48, v49
	v_add_f32_e32 v175, v175, v34
	v_add_f32_e32 v174, v174, v50
	v_add_f32_e32 v175, v175, v35
	v_add_f32_e32 v174, v174, v51
	v_add_f32_e32 v175, v175, v36
	v_add_f32_e32 v174, v174, v52
	v_add_f32_e32 v175, v175, v37
	v_add_f32_e32 v174, v174, v53
	v_add_f32_e32 v175, v175, v38
	v_add_f32_e32 v174, v174, v54
	v_add_f32_e32 v175, v175, v39
	v_add_f32_e32 v174, v174, v55
	v_add_f32_e32 v175, v175, v40
	v_add_f32_e32 v174, v174, v56
	v_add_f32_e32 v175, v175, v41
	v_add_f32_e32 v174, v174, v57
	v_add_f32_e32 v175, v175, v42
	v_add_f32_e32 v174, v174, v58
	v_add_f32_e32 v175, v175, v43
	v_add_f32_e32 v174, v174, v59
	v_add_f32_e32 v175, v175, v44
	v_add_f32_e32 v174, v174, v60
	v_add_f32_e32 v175, v175, v45
	v_add_f32_e32 v174, v174, v61
	v_add_f32_e32 v175, v175, v46
	v_add_f32_e32 v174, v174, v62
	v_add_f32_e32 v175, v175, v47
	v_add_f32_e32 v174, v174, v63
	v_add_f32_e32 v175, v175, v174
	v_cmp_ge_f32_e32 vcc, s23, v175
	s_cmp_eq_u64 vcc, exec
	s_cbranch_scc0 .Lat_rare_t131
